# v091 + layer-1 adaLN GEMV executed by the retention workgroups during layer 0's mixer phase (3 units each); layer-1 modulation phase skips it
# baseline (speedup 1.0000x reference)
.Lmy_a_entry:
	s_waitcnt vmcnt(0)
	v_mov_b32_e32 v8, v0
	s_mov_b64 s[6:7], s[70:71]
	s_load_dwordx2 s[4:5], s[6:7], 0xe0
	v_readlane_b32 s8, v253, 3
	v_readfirstlane_b32 s0, v8
	v_readlane_b32 s9, v253, 4
	v_and_b32_e32 v16, 63, v8
	s_cmp_eq_u32 s100, 1
	s_cbranch_scc1 .Lmy_a_zero
	s_cmp_eq_u32 s100, 0
	s_cbranch_scc0 .Lmy_a_keep
	s_cmpk_lg_i32 s3, 0x100
	s_cbranch_scc1 .Lmy_a_keep
	v_readlane_b32 s2, v255, 8
	s_nop 3
	s_cmp_eq_u32 s2, 1
	s_cbranch_scc0 .Lmy_a_keep
.Lmy_a_zero:
	s_nop 3
	s_mov_b64 s[8:9], 0
.Lmy_a_keep:
	s_andn2_b64 vcc, exec, s[8:9]
	s_ashr_i32 s30, s0, 6
	s_cbranch_vccnz .LBB0_37
	v_ashrrev_i32_e32 v2, 31, v8
	v_lshrrev_b32_e32 v2, 26, v2
	s_waitcnt lgkmcnt(0)
	v_readlane_b32 s12, v255, 8
	v_add_u32_e32 v2, v8, v2
	s_load_dwordx4 s[48:51], s[6:7], 0x28
	s_load_dwordx2 s[8:9], s[6:7], 0x8
	s_load_dwordx2 s[10:11], s[6:7], 0x18
	s_mov_b32 s42, s12
	v_ashrrev_i32_e32 v6, 6, v2
	v_and_b32_e32 v2, 0xffffffc0, v2
	v_mad_u64_u32 v[4:5], s[42:43], s42, 5, v[6:7]
	s_mul_i32 s0, s12, 0xc000
	v_sub_u32_e32 v2, v8, v2
	s_waitcnt lgkmcnt(0)
	v_mov_b64_e32 v[10:11], s[4:5]
	s_mov_b32 s42, 0xc000
	v_readlane_b32 s13, v255, 9
	s_mul_i32 s46, s12, 0xc000000
	s_add_u32 s12, s50, s0
	v_ashrrev_i32_e32 v3, 31, v2
	v_mad_i64_i32 v[4:5], s[42:43], v4, s42, v[10:11]
	s_addc_u32 s13, s51, 0
	s_movk_i32 s0, 0x5000
	s_lshl_b32 s2, s30, 11
	s_mul_i32 s40, s30, 0x500
	v_lshl_add_u64 v[4:5], v[2:3], 2, v[4:5]
	v_max_i32_e32 v3, 0x4e00, v8
	v_cmp_gt_i32_e64 s[38:39], s0, v8
	s_lshl_b32 s0, s30, 9
	s_add_i32 s2, s2, 0
	s_add_i32 s40, s14, s40
	v_sub_u32_e32 v3, v3, v8
	s_mul_i32 s47, s30, 0x1800000
	v_add_u32_e32 v3, 0x1ff, v3
	s_mul_hi_i32 s0, s0, 0xc000
	s_add_u32 s46, s46, s47
	v_lshlrev_b32_e32 v10, 8, v6
	v_lshrrev_b32_e32 v6, 9, v3
	s_addc_u32 s0, 0, s0
	s_mov_b64 s[42:43], 0xaf40000
	v_add_u32_e32 v6, 1, v6
	s_add_u32 s46, s48, s46
	v_lshlrev_b32_e32 v194, 2, v16
	v_lshl_add_u64 v[4:5], v[4:5], 0, s[42:43]
	v_cmp_lt_u32_e64 s[42:43], s15, v3
	v_and_b32_e32 v3, 0xfffffe, v6
	s_addc_u32 s47, s49, s0
	v_add_u32_e32 v17, s40, v194
	s_movk_i32 s40, 0x140
	v_lshl_add_u32 v12, v2, 2, s14
	v_cmp_ne_u32_e64 s[44:45], v6, v3
	v_lshl_add_u64 v[6:7], s[46:47], 0, v[194:195]
	s_mov_b64 s[46:47], 0x54000
	v_readlane_b32 s0, v254, 30
	v_cmp_gt_i32_e64 s[40:41], s40, v8
	v_lshl_add_u32 v18, v3, 9, v8
	v_add_u32_e32 v9, 0x200, v8
	v_lshl_add_u32 v19, v8, 2, 0
	v_lshl_add_u64 v[6:7], v[6:7], 0, s[46:47]
	s_mov_b64 s[46:47], 0
	v_add_u32_e32 v20, v12, v10
	s_mov_b32 s48, s0
	s_mov_b32 s56, s76
	s_cmp_eq_u32 s100, 3
	s_cbranch_scc0 .Lmy_g_nou
	s_mov_b32 s56, s101
	s_lshl_b32 s48, s101, 6
.Lmy_g_nou:
	s_branch .LBB0_17
.LBB0_16:
	s_or_b64 exec, exec, s[46:47]
	v_readlane_b32 s0, v254, 31
	s_add_i32 s56, s56, s3
	s_add_i32 s48, s48, s0
	s_cmpk_gt_i32 s56, 0xbf
	s_mov_b64 s[46:47], -1
	s_barrier
	s_cbranch_scc1 .LBB0_37

.LBB0_37:
	s_cmp_eq_u32 s100, 3
	s_cbranch_scc1 .Lmy_tr_dret
	v_readlane_b32 s0, v253, 5
	s_add_i32 s2, s30, s0
	s_movk_i32 s101, 0x4540
	s_cmp_eq_u32 s100, 1
	s_cbranch_scc1 .Lmy_a_def
	s_cmpk_lg_i32 s3, 0x100
	s_cbranch_scc1 .Lmy_a_it
	s_movk_i32 s101, 0x3440
	s_branch .Lmy_a_it

.Lpb_next:
	s_add_i32 s65, s65, s3
	s_cmpk_lt_i32 s65, 0x440
	s_cbranch_scc1 .Lpb_loop
	s_branch .LBB0_178
	s_nop 0
	s_nop 0
	s_nop 0
	s_nop 0
	s_nop 0
	s_nop 0
	s_nop 0
	s_nop 0
	s_nop 0
	s_nop 0
	s_nop 0
	s_nop 0
	s_nop 0
	s_nop 0
	s_nop 0
	s_nop 0
	s_nop 0
	s_nop 0
	s_nop 0
	s_nop 0
	s_nop 0
	s_branch .LBB0_178
.LBB0_178:
	v_readlane_b32 s0, v255, 10
	v_readlane_b32 s60, v255, 0
	s_add_i32 s0, s0, 2
	v_readlane_b32 s63, v255, 3
	v_readlane_b32 s62, v255, 2
	s_cmp_ge_i32 s0, s63
	s_barrier
	v_readlane_b32 s61, v255, 1
	s_cbranch_scc1 .LBB0_190
	s_waitcnt vmcnt(0)
	s_barrier
	s_mov_b64 s[4:5], exec
	v_readlane_b32 s6, v254, 56
	v_readlane_b32 s7, v254, 57
	v_readlane_b32 s60, v255, 6
	s_and_b64 s[6:7], s[4:5], s[6:7]
	v_readlane_b32 s61, v255, 7
	s_mov_b64 exec, s[6:7]
	s_cbranch_execz .LBB0_228
	v_readlane_b32 s2, v253, 2
	s_waitcnt vmcnt(0) expcnt(0) lgkmcnt(0)
	s_nop 0
	v_mov_b32_e32 v2, s2
	ds_read_b32 v4, v2
	ds_read_b32 v2, v2 offset:4
	s_waitcnt lgkmcnt(1)
	v_cmp_ne_u32_e32 vcc, 0, v4
	s_cbranch_vccnz .LBB0_196
	v_readlane_b32 s8, v253, 0
	v_readlane_b32 s9, v253, 1
	s_load_dwordx2 s[6:7], s[8:9], 0x4
	s_mov_b32 s12, 1
	s_waitcnt lgkmcnt(0)
	s_mul_i32 s2, s6, s3
	s_mul_i32 s2, s2, s7
	s_branch .LBB0_183

.LBB0_248:
	v_readlane_b32 s0, v255, 10
	s_add_i32 s0, s0, 3
	s_cmp_ge_i32 s0, s63
	s_cbranch_scc1 .LBB0_298
	s_waitcnt vmcnt(0)
	s_waitcnt vmcnt(0)
	s_barrier
	s_mov_b64 s[4:5], exec
	v_readlane_b32 s6, v254, 56
	v_readlane_b32 s7, v254, 57
	s_and_b64 s[6:7], s[4:5], s[6:7]
	s_mov_b64 exec, s[6:7]
	s_cbranch_execz .LBB0_297
	v_readlane_b32 s2, v253, 2
	s_waitcnt vmcnt(0) expcnt(0) lgkmcnt(0)
	s_nop 0
	v_mov_b32_e32 v2, s2
	ds_read_b32 v4, v2
	ds_read_b32 v2, v2 offset:4
	s_waitcnt lgkmcnt(1)
	v_cmp_ne_u32_e32 vcc, 0, v4
	s_cbranch_vccnz .LBB0_265
	v_readlane_b32 s8, v253, 0
	v_readlane_b32 s9, v253, 1
	s_load_dwordx2 s[6:7], s[8:9], 0x4
	s_mov_b32 s12, 1
	s_waitcnt lgkmcnt(0)
	s_mul_i32 s2, s6, s3
	s_mul_i32 s2, s2, s7
	s_branch .LBB0_253
.Lmy_tr_acall:
	s_branch .Lmy_a_entry
.Lmy_tr_dret:
	s_branch .Lmy_d_ret
.LBB0_252:
	s_and_b64 vcc, exec, s[8:9]
	s_cbranch_vccnz .LBB0_260

.LBB0_566:
	v_readlane_b32 s0, v255, 8
	s_nop 3
	s_cmp_lg_u32 s0, 0
	s_cbranch_scc1 .Lmy_d_nocall
	s_cmpk_lg_i32 s3, 0x100
	s_cbranch_scc1 .Lmy_d_nocall
	s_cmpk_lt_i32 s76, 0x80
	s_cbranch_scc1 .Lmy_d_nocall
	s_cmpk_gt_i32 s76, 0xbf
	s_cbranch_scc1 .Lmy_d_nocall
	s_mov_b32 s100, 3
	s_mov_b32 s0, 1
	v_writelane_b32 v255, s0, 8
	s_add_i32 s101, s76, 0xffffff80
	s_waitcnt vmcnt(0) lgkmcnt(0)
	s_barrier

.Lmy_d_ret:
	s_add_i32 s101, s101, 64
	s_cmpk_lt_i32 s101, 0xc0
	s_cbranch_scc1 .Lmy_d_loop
	s_mov_b32 s100, 0
	s_mov_b32 s0, 0
	v_writelane_b32 v255, s0, 8
	s_nop 1

.LBB0_695:
	v_lshl_add_u32 v148, s6, 8, v150
	s_lshl_b32 s0, s4, 8
	v_or_b32_e32 v149, s0, v152
	v_mov_b32_e32 v181, 0
	v_lshlrev_b32_e32 v180, 11, v148
	v_lshl_add_u32 v180, v149, 1, v180
	v_lshl_add_u64 v[142:143], s[40:41], 0, v[180:181]
	v_lshlrev_b32_e32 v180, 2, v149
	v_lshl_add_u64 v[178:179], s[46:47], 0, v[180:181]
	global_load_dwordx4 v[154:157], v[178:179], off
	global_load_dwordx4 v[158:161], v[178:179], off offset:16
	global_load_dwordx4 v[162:165], v[178:179], off offset:512
	global_load_dwordx4 v[166:169], v[178:179], off offset:528
	s_add_i32 s4, s0, 0x2400
	s_ashr_i32 s0, s4, 9
	s_mul_hi_i32 s4, s0, 0x1100000
	s_mul_i32 s0, s0, 0x1100000
	s_add_u32 s58, s65, s0
	s_addc_u32 s59, s66, s4
	v_and_b32_e32 v180, 0x1ff, v149
	v_lshlrev_b32_e32 v180, 1, v180
	v_lshl_add_u32 v180, v148, 10, v180
	v_lshl_add_u64 v[144:145], s[58:59], 0, v[180:181]
	v_lshlrev_b32_e32 v180, 13, v148
	v_lshl_add_u32 v180, v149, 1, v180
	v_add_u32_e32 v180, 0x1000, v180
	v_lshl_add_u64 v[146:147], s[44:45], 0, v[180:181]
	global_load_dwordx4 v[170:173], v[142:143], off
	global_load_dwordx4 v[174:177], v[144:145], off
	s_waitcnt vmcnt(2)
	v_pk_add_f32 v[126:127], v[126:127], v[154:155]
	v_pk_add_f32 v[122:123], v[122:123], v[158:159]
	v_pk_add_f32 v[128:129], v[128:129], v[156:157]
	v_pk_add_f32 v[124:125], v[124:125], v[160:161]
	v_pk_add_f32 v[118:119], v[118:119], v[162:163]
	v_pk_add_f32 v[114:115], v[114:115], v[166:167]
	v_pk_add_f32 v[120:121], v[120:121], v[164:165]
	v_pk_add_f32 v[116:117], v[116:117], v[168:169]
	v_pk_add_f32 v[110:111], v[110:111], v[154:155]
	v_pk_add_f32 v[106:107], v[106:107], v[158:159]
	v_pk_add_f32 v[112:113], v[112:113], v[156:157]
	v_pk_add_f32 v[108:109], v[108:109], v[160:161]
	v_pk_add_f32 v[102:103], v[102:103], v[162:163]
	v_pk_add_f32 v[98:99], v[98:99], v[166:167]
	v_pk_add_f32 v[104:105], v[104:105], v[164:165]
	v_pk_add_f32 v[100:101], v[100:101], v[168:169]
	v_pk_add_f32 v[94:95], v[94:95], v[154:155]
	v_pk_add_f32 v[90:91], v[90:91], v[158:159]
	v_pk_add_f32 v[96:97], v[96:97], v[156:157]
	v_pk_add_f32 v[92:93], v[92:93], v[160:161]
	v_pk_add_f32 v[86:87], v[86:87], v[162:163]
	v_pk_add_f32 v[82:83], v[82:83], v[166:167]
	v_pk_add_f32 v[88:89], v[88:89], v[164:165]
	v_pk_add_f32 v[84:85], v[84:85], v[168:169]
	v_pk_add_f32 v[78:79], v[78:79], v[154:155]
	v_pk_add_f32 v[74:75], v[74:75], v[158:159]
	v_pk_add_f32 v[80:81], v[80:81], v[156:157]
	v_pk_add_f32 v[76:77], v[76:77], v[160:161]
	v_pk_add_f32 v[70:71], v[70:71], v[162:163]
	v_pk_add_f32 v[66:67], v[66:67], v[166:167]
	v_pk_add_f32 v[72:73], v[72:73], v[164:165]
	v_pk_add_f32 v[68:69], v[68:69], v[168:169]
	v_pk_add_f32 v[62:63], v[62:63], v[154:155]
	v_pk_add_f32 v[58:59], v[58:59], v[158:159]
	v_pk_add_f32 v[64:65], v[64:65], v[156:157]
	v_pk_add_f32 v[60:61], v[60:61], v[160:161]
	v_pk_add_f32 v[54:55], v[54:55], v[162:163]
	v_pk_add_f32 v[50:51], v[50:51], v[166:167]
	v_pk_add_f32 v[56:57], v[56:57], v[164:165]
	v_pk_add_f32 v[52:53], v[52:53], v[168:169]
	v_pk_add_f32 v[46:47], v[46:47], v[154:155]
	v_pk_add_f32 v[42:43], v[42:43], v[158:159]
	v_pk_add_f32 v[48:49], v[48:49], v[156:157]
	v_pk_add_f32 v[44:45], v[44:45], v[160:161]
	v_pk_add_f32 v[38:39], v[38:39], v[162:163]
	v_pk_add_f32 v[34:35], v[34:35], v[166:167]
	v_pk_add_f32 v[40:41], v[40:41], v[164:165]
	v_pk_add_f32 v[36:37], v[36:37], v[168:169]
	v_pk_add_f32 v[30:31], v[30:31], v[154:155]
	v_pk_add_f32 v[26:27], v[26:27], v[158:159]
	v_pk_add_f32 v[32:33], v[32:33], v[156:157]
	v_pk_add_f32 v[28:29], v[28:29], v[160:161]
	v_pk_add_f32 v[22:23], v[22:23], v[162:163]
	v_pk_add_f32 v[18:19], v[18:19], v[166:167]
	v_pk_add_f32 v[24:25], v[24:25], v[164:165]
	v_pk_add_f32 v[20:21], v[20:21], v[168:169]
	v_pk_add_f32 v[14:15], v[14:15], v[154:155]
	v_pk_add_f32 v[10:11], v[10:11], v[158:159]
	v_pk_add_f32 v[16:17], v[16:17], v[156:157]
	v_pk_add_f32 v[12:13], v[12:13], v[160:161]
	v_pk_add_f32 v[6:7], v[6:7], v[162:163]
	v_pk_add_f32 v[2:3], v[2:3], v[166:167]
	v_pk_add_f32 v[8:9], v[8:9], v[164:165]
	v_pk_add_f32 v[4:5], v[4:5], v[168:169]
	global_load_dwordx4 v[154:157], v[142:143], off offset:256
	global_load_dwordx4 v[158:161], v[144:145], off offset:256
	s_mov_b64 s[58:59], 0x8000
	v_lshl_add_u64 v[142:143], v[142:143], 0, s[58:59]
	s_mov_b64 s[58:59], 0x4000
	v_lshl_add_u64 v[144:145], v[144:145], 0, s[58:59]
	global_load_dwordx4 v[162:165], v[142:143], off
	global_load_dwordx4 v[166:169], v[144:145], off
	s_waitcnt vmcnt(4)
	v_lshlrev_b32_e32 v178, 16, v170
	v_and_b32_e32 v170, 0xffff0000, v170
	v_lshlrev_b32_e32 v179, 16, v174
	v_and_b32_e32 v174, 0xffff0000, v174
	v_mul_f32_e32 v126, 0xbfb8aa3b, v126
	v_mul_f32_e32 v127, 0xbfb8aa3b, v127
	v_mul_f32_e32 v180, 0xbfb8aa3b, v179
	v_mul_f32_e32 v181, 0xbfb8aa3b, v174
	v_exp_f32_e32 v126, v126
	v_exp_f32_e32 v127, v127
	v_exp_f32_e32 v180, v180
	v_exp_f32_e32 v181, v181
	v_add_f32_e32 v126, 1.0, v126
	v_add_f32_e32 v127, 1.0, v127
	v_add_f32_e32 v180, 1.0, v180
	v_add_f32_e32 v181, 1.0, v181
	v_rcp_f32_e32 v126, v126
	v_rcp_f32_e32 v127, v127
	v_rcp_f32_e32 v180, v180
	v_rcp_f32_e32 v181, v181
	v_mul_f32_e32 v126, v126, v178
	v_mul_f32_e32 v127, v127, v170
	v_mul_f32_e32 v180, v180, v179
	v_mul_f32_e32 v181, v181, v174
	v_mul_f32_e32 v126, v126, v180
	v_mul_f32_e32 v127, v127, v181
	v_lshlrev_b32_e32 v178, 16, v171
	v_and_b32_e32 v171, 0xffff0000, v171
	v_lshlrev_b32_e32 v179, 16, v175
	v_and_b32_e32 v175, 0xffff0000, v175
	v_mul_f32_e32 v128, 0xbfb8aa3b, v128
	v_mul_f32_e32 v129, 0xbfb8aa3b, v129
	v_mul_f32_e32 v180, 0xbfb8aa3b, v179
	v_mul_f32_e32 v181, 0xbfb8aa3b, v175
	v_exp_f32_e32 v128, v128
	v_exp_f32_e32 v129, v129
	v_exp_f32_e32 v180, v180
	v_exp_f32_e32 v181, v181
	v_add_f32_e32 v128, 1.0, v128
	v_add_f32_e32 v129, 1.0, v129
	v_add_f32_e32 v180, 1.0, v180
	v_add_f32_e32 v181, 1.0, v181
	v_rcp_f32_e32 v128, v128
	v_rcp_f32_e32 v129, v129
	v_rcp_f32_e32 v180, v180
	v_rcp_f32_e32 v181, v181
	v_mul_f32_e32 v128, v128, v178
	v_mul_f32_e32 v129, v129, v171
	v_mul_f32_e32 v180, v180, v179
	v_mul_f32_e32 v181, v181, v175
	v_mul_f32_e32 v128, v128, v180
	v_mul_f32_e32 v129, v129, v181
	v_lshlrev_b32_e32 v178, 16, v172
	v_and_b32_e32 v172, 0xffff0000, v172
	v_lshlrev_b32_e32 v179, 16, v176
	v_and_b32_e32 v176, 0xffff0000, v176
	v_mul_f32_e32 v122, 0xbfb8aa3b, v122
	v_mul_f32_e32 v123, 0xbfb8aa3b, v123
	v_mul_f32_e32 v180, 0xbfb8aa3b, v179
	v_mul_f32_e32 v181, 0xbfb8aa3b, v176
	v_exp_f32_e32 v122, v122
	v_exp_f32_e32 v123, v123
	v_exp_f32_e32 v180, v180
	v_exp_f32_e32 v181, v181
	v_add_f32_e32 v122, 1.0, v122
	v_add_f32_e32 v123, 1.0, v123
	v_add_f32_e32 v180, 1.0, v180
	v_add_f32_e32 v181, 1.0, v181
	v_rcp_f32_e32 v122, v122
	v_rcp_f32_e32 v123, v123
	v_rcp_f32_e32 v180, v180
	v_rcp_f32_e32 v181, v181
	v_mul_f32_e32 v122, v122, v178
	v_mul_f32_e32 v123, v123, v172
	v_mul_f32_e32 v180, v180, v179
	v_mul_f32_e32 v181, v181, v176
	v_mul_f32_e32 v122, v122, v180
	v_mul_f32_e32 v123, v123, v181
	v_lshlrev_b32_e32 v178, 16, v173
	v_and_b32_e32 v173, 0xffff0000, v173
	v_lshlrev_b32_e32 v179, 16, v177
	v_and_b32_e32 v177, 0xffff0000, v177
	v_mul_f32_e32 v124, 0xbfb8aa3b, v124
	v_mul_f32_e32 v125, 0xbfb8aa3b, v125
	v_mul_f32_e32 v180, 0xbfb8aa3b, v179
	v_mul_f32_e32 v181, 0xbfb8aa3b, v177
	v_exp_f32_e32 v124, v124
	v_exp_f32_e32 v125, v125
	v_exp_f32_e32 v180, v180
	v_exp_f32_e32 v181, v181
	v_add_f32_e32 v124, 1.0, v124
	v_add_f32_e32 v125, 1.0, v125
	v_add_f32_e32 v180, 1.0, v180
	v_add_f32_e32 v181, 1.0, v181
	v_rcp_f32_e32 v124, v124
	v_rcp_f32_e32 v125, v125
	v_rcp_f32_e32 v180, v180
	v_rcp_f32_e32 v181, v181
	v_mul_f32_e32 v124, v124, v178
	v_mul_f32_e32 v125, v125, v173
	v_mul_f32_e32 v180, v180, v179
	v_mul_f32_e32 v181, v181, v177
	v_mul_f32_e32 v124, v124, v180
	v_mul_f32_e32 v125, v125, v181
	v_cvt_pk_bf16_f32 v126, v126, v127
	v_cvt_pk_bf16_f32 v127, v128, v129
	v_cvt_pk_bf16_f32 v128, v122, v123
	v_cvt_pk_bf16_f32 v129, v124, v125
	global_store_dwordx4 v[146:147], v[126:129], off
	global_load_dwordx4 v[170:173], v[142:143], off offset:256
	global_load_dwordx4 v[174:177], v[144:145], off offset:256
	s_waitcnt vmcnt(5)
	v_lshlrev_b32_e32 v178, 16, v154
	v_and_b32_e32 v154, 0xffff0000, v154
	v_lshlrev_b32_e32 v179, 16, v158
	v_and_b32_e32 v158, 0xffff0000, v158
	v_mul_f32_e32 v118, 0xbfb8aa3b, v118
	v_mul_f32_e32 v119, 0xbfb8aa3b, v119
	v_mul_f32_e32 v180, 0xbfb8aa3b, v179
	v_mul_f32_e32 v181, 0xbfb8aa3b, v158
	v_exp_f32_e32 v118, v118
	v_exp_f32_e32 v119, v119
	v_exp_f32_e32 v180, v180
	v_exp_f32_e32 v181, v181
	v_add_f32_e32 v118, 1.0, v118
	v_add_f32_e32 v119, 1.0, v119
	v_add_f32_e32 v180, 1.0, v180
	v_add_f32_e32 v181, 1.0, v181
	v_rcp_f32_e32 v118, v118
	v_rcp_f32_e32 v119, v119
	v_rcp_f32_e32 v180, v180
	v_rcp_f32_e32 v181, v181
	v_mul_f32_e32 v118, v118, v178
	v_mul_f32_e32 v119, v119, v154
	v_mul_f32_e32 v180, v180, v179
	v_mul_f32_e32 v181, v181, v158
	v_mul_f32_e32 v118, v118, v180
	v_mul_f32_e32 v119, v119, v181
	v_lshlrev_b32_e32 v178, 16, v155
	v_and_b32_e32 v155, 0xffff0000, v155
	v_lshlrev_b32_e32 v179, 16, v159
	v_and_b32_e32 v159, 0xffff0000, v159
	v_mul_f32_e32 v120, 0xbfb8aa3b, v120
	v_mul_f32_e32 v121, 0xbfb8aa3b, v121
	v_mul_f32_e32 v180, 0xbfb8aa3b, v179
	v_mul_f32_e32 v181, 0xbfb8aa3b, v159
	v_exp_f32_e32 v120, v120
	v_exp_f32_e32 v121, v121
	v_exp_f32_e32 v180, v180
	v_exp_f32_e32 v181, v181
	v_add_f32_e32 v120, 1.0, v120
	v_add_f32_e32 v121, 1.0, v121
	v_add_f32_e32 v180, 1.0, v180
	v_add_f32_e32 v181, 1.0, v181
	v_rcp_f32_e32 v120, v120
	v_rcp_f32_e32 v121, v121
	v_rcp_f32_e32 v180, v180
	v_rcp_f32_e32 v181, v181
	v_mul_f32_e32 v120, v120, v178
	v_mul_f32_e32 v121, v121, v155
	v_mul_f32_e32 v180, v180, v179
	v_mul_f32_e32 v181, v181, v159
	v_mul_f32_e32 v120, v120, v180
	v_mul_f32_e32 v121, v121, v181
	v_lshlrev_b32_e32 v178, 16, v156
	v_and_b32_e32 v156, 0xffff0000, v156
	v_lshlrev_b32_e32 v179, 16, v160
	v_and_b32_e32 v160, 0xffff0000, v160
	v_mul_f32_e32 v114, 0xbfb8aa3b, v114
	v_mul_f32_e32 v115, 0xbfb8aa3b, v115
	v_mul_f32_e32 v180, 0xbfb8aa3b, v179
	v_mul_f32_e32 v181, 0xbfb8aa3b, v160
	v_exp_f32_e32 v114, v114
	v_exp_f32_e32 v115, v115
	v_exp_f32_e32 v180, v180
	v_exp_f32_e32 v181, v181
	v_add_f32_e32 v114, 1.0, v114
	v_add_f32_e32 v115, 1.0, v115
	v_add_f32_e32 v180, 1.0, v180
	v_add_f32_e32 v181, 1.0, v181
	v_rcp_f32_e32 v114, v114
	v_rcp_f32_e32 v115, v115
	v_rcp_f32_e32 v180, v180
	v_rcp_f32_e32 v181, v181
	v_mul_f32_e32 v114, v114, v178
	v_mul_f32_e32 v115, v115, v156
	v_mul_f32_e32 v180, v180, v179
	v_mul_f32_e32 v181, v181, v160
	v_mul_f32_e32 v114, v114, v180
	v_mul_f32_e32 v115, v115, v181
	v_lshlrev_b32_e32 v178, 16, v157
	v_and_b32_e32 v157, 0xffff0000, v157
	v_lshlrev_b32_e32 v179, 16, v161
	v_and_b32_e32 v161, 0xffff0000, v161
	v_mul_f32_e32 v116, 0xbfb8aa3b, v116
	v_mul_f32_e32 v117, 0xbfb8aa3b, v117
	v_mul_f32_e32 v180, 0xbfb8aa3b, v179
	v_mul_f32_e32 v181, 0xbfb8aa3b, v161
	v_exp_f32_e32 v116, v116
	v_exp_f32_e32 v117, v117
	v_exp_f32_e32 v180, v180
	v_exp_f32_e32 v181, v181
	v_add_f32_e32 v116, 1.0, v116
	v_add_f32_e32 v117, 1.0, v117
	v_add_f32_e32 v180, 1.0, v180
	v_add_f32_e32 v181, 1.0, v181
	v_rcp_f32_e32 v116, v116
	v_rcp_f32_e32 v117, v117
	v_rcp_f32_e32 v180, v180
	v_rcp_f32_e32 v181, v181
	v_mul_f32_e32 v116, v116, v178
	v_mul_f32_e32 v117, v117, v157
	v_mul_f32_e32 v180, v180, v179
	v_mul_f32_e32 v181, v181, v161
	v_mul_f32_e32 v116, v116, v180
	v_mul_f32_e32 v117, v117, v181
	v_cvt_pk_bf16_f32 v118, v118, v119
	v_cvt_pk_bf16_f32 v119, v120, v121
	v_cvt_pk_bf16_f32 v120, v114, v115
	v_cvt_pk_bf16_f32 v121, v116, v117
	global_store_dwordx4 v[146:147], v[118:121], off offset:256
	s_mov_b64 s[58:59], 0x20000
	v_lshl_add_u64 v[146:147], v[146:147], 0, s[58:59]
	s_mov_b64 s[58:59], 0x8000
	v_lshl_add_u64 v[142:143], v[142:143], 0, s[58:59]
	s_mov_b64 s[58:59], 0x4000
	v_lshl_add_u64 v[144:145], v[144:145], 0, s[58:59]
	global_load_dwordx4 v[154:157], v[142:143], off
	global_load_dwordx4 v[158:161], v[144:145], off
	s_waitcnt vmcnt(6)
	v_lshlrev_b32_e32 v178, 16, v162
	v_and_b32_e32 v162, 0xffff0000, v162
	v_lshlrev_b32_e32 v179, 16, v166
	v_and_b32_e32 v166, 0xffff0000, v166
	v_mul_f32_e32 v110, 0xbfb8aa3b, v110
	v_mul_f32_e32 v111, 0xbfb8aa3b, v111
	v_mul_f32_e32 v180, 0xbfb8aa3b, v179
	v_mul_f32_e32 v181, 0xbfb8aa3b, v166
	v_exp_f32_e32 v110, v110
	v_exp_f32_e32 v111, v111
	v_exp_f32_e32 v180, v180
	v_exp_f32_e32 v181, v181
	v_add_f32_e32 v110, 1.0, v110
	v_add_f32_e32 v111, 1.0, v111
	v_add_f32_e32 v180, 1.0, v180
	v_add_f32_e32 v181, 1.0, v181
	v_rcp_f32_e32 v110, v110
	v_rcp_f32_e32 v111, v111
	v_rcp_f32_e32 v180, v180
	v_rcp_f32_e32 v181, v181
	v_mul_f32_e32 v110, v110, v178
	v_mul_f32_e32 v111, v111, v162
	v_mul_f32_e32 v180, v180, v179
	v_mul_f32_e32 v181, v181, v166
	v_mul_f32_e32 v110, v110, v180
	v_mul_f32_e32 v111, v111, v181
	v_lshlrev_b32_e32 v178, 16, v163
	v_and_b32_e32 v163, 0xffff0000, v163
	v_lshlrev_b32_e32 v179, 16, v167
	v_and_b32_e32 v167, 0xffff0000, v167
	v_mul_f32_e32 v112, 0xbfb8aa3b, v112
	v_mul_f32_e32 v113, 0xbfb8aa3b, v113
	v_mul_f32_e32 v180, 0xbfb8aa3b, v179
	v_mul_f32_e32 v181, 0xbfb8aa3b, v167
	v_exp_f32_e32 v112, v112
	v_exp_f32_e32 v113, v113
	v_exp_f32_e32 v180, v180
	v_exp_f32_e32 v181, v181
	v_add_f32_e32 v112, 1.0, v112
	v_add_f32_e32 v113, 1.0, v113
	v_add_f32_e32 v180, 1.0, v180
	v_add_f32_e32 v181, 1.0, v181
	v_rcp_f32_e32 v112, v112
	v_rcp_f32_e32 v113, v113
	v_rcp_f32_e32 v180, v180
	v_rcp_f32_e32 v181, v181
	v_mul_f32_e32 v112, v112, v178
	v_mul_f32_e32 v113, v113, v163
	v_mul_f32_e32 v180, v180, v179
	v_mul_f32_e32 v181, v181, v167
	v_mul_f32_e32 v112, v112, v180
	v_mul_f32_e32 v113, v113, v181
	v_lshlrev_b32_e32 v178, 16, v164
	v_and_b32_e32 v164, 0xffff0000, v164
	v_lshlrev_b32_e32 v179, 16, v168
	v_and_b32_e32 v168, 0xffff0000, v168
	v_mul_f32_e32 v106, 0xbfb8aa3b, v106
	v_mul_f32_e32 v107, 0xbfb8aa3b, v107
	v_mul_f32_e32 v180, 0xbfb8aa3b, v179
	v_mul_f32_e32 v181, 0xbfb8aa3b, v168
	v_exp_f32_e32 v106, v106
	v_exp_f32_e32 v107, v107
	v_exp_f32_e32 v180, v180
	v_exp_f32_e32 v181, v181
	v_add_f32_e32 v106, 1.0, v106
	v_add_f32_e32 v107, 1.0, v107
	v_add_f32_e32 v180, 1.0, v180
	v_add_f32_e32 v181, 1.0, v181
	v_rcp_f32_e32 v106, v106
	v_rcp_f32_e32 v107, v107
	v_rcp_f32_e32 v180, v180
	v_rcp_f32_e32 v181, v181
	v_mul_f32_e32 v106, v106, v178
	v_mul_f32_e32 v107, v107, v164
	v_mul_f32_e32 v180, v180, v179
	v_mul_f32_e32 v181, v181, v168
	v_mul_f32_e32 v106, v106, v180
	v_mul_f32_e32 v107, v107, v181
	v_lshlrev_b32_e32 v178, 16, v165
	v_and_b32_e32 v165, 0xffff0000, v165
	v_lshlrev_b32_e32 v179, 16, v169
	v_and_b32_e32 v169, 0xffff0000, v169
	v_mul_f32_e32 v108, 0xbfb8aa3b, v108
	v_mul_f32_e32 v109, 0xbfb8aa3b, v109
	v_mul_f32_e32 v180, 0xbfb8aa3b, v179
	v_mul_f32_e32 v181, 0xbfb8aa3b, v169
	v_exp_f32_e32 v108, v108
	v_exp_f32_e32 v109, v109
	v_exp_f32_e32 v180, v180
	v_exp_f32_e32 v181, v181
	v_add_f32_e32 v108, 1.0, v108
	v_add_f32_e32 v109, 1.0, v109
	v_add_f32_e32 v180, 1.0, v180
	v_add_f32_e32 v181, 1.0, v181
	v_rcp_f32_e32 v108, v108
	v_rcp_f32_e32 v109, v109
	v_rcp_f32_e32 v180, v180
	v_rcp_f32_e32 v181, v181
	v_mul_f32_e32 v108, v108, v178
	v_mul_f32_e32 v109, v109, v165
	v_mul_f32_e32 v180, v180, v179
	v_mul_f32_e32 v181, v181, v169
	v_mul_f32_e32 v108, v108, v180
	v_mul_f32_e32 v109, v109, v181
	v_cvt_pk_bf16_f32 v110, v110, v111
	v_cvt_pk_bf16_f32 v111, v112, v113
	v_cvt_pk_bf16_f32 v112, v106, v107
	v_cvt_pk_bf16_f32 v113, v108, v109
	global_store_dwordx4 v[146:147], v[110:113], off
	global_load_dwordx4 v[162:165], v[142:143], off offset:256
	global_load_dwordx4 v[166:169], v[144:145], off offset:256
	s_waitcnt vmcnt(6)
	v_lshlrev_b32_e32 v178, 16, v170
	v_and_b32_e32 v170, 0xffff0000, v170
	v_lshlrev_b32_e32 v179, 16, v174
	v_and_b32_e32 v174, 0xffff0000, v174
	v_mul_f32_e32 v102, 0xbfb8aa3b, v102
	v_mul_f32_e32 v103, 0xbfb8aa3b, v103
	v_mul_f32_e32 v180, 0xbfb8aa3b, v179
	v_mul_f32_e32 v181, 0xbfb8aa3b, v174
	v_exp_f32_e32 v102, v102
	v_exp_f32_e32 v103, v103
	v_exp_f32_e32 v180, v180
	v_exp_f32_e32 v181, v181
	v_add_f32_e32 v102, 1.0, v102
	v_add_f32_e32 v103, 1.0, v103
	v_add_f32_e32 v180, 1.0, v180
	v_add_f32_e32 v181, 1.0, v181
	v_rcp_f32_e32 v102, v102
	v_rcp_f32_e32 v103, v103
	v_rcp_f32_e32 v180, v180
	v_rcp_f32_e32 v181, v181
	v_mul_f32_e32 v102, v102, v178
	v_mul_f32_e32 v103, v103, v170
	v_mul_f32_e32 v180, v180, v179
	v_mul_f32_e32 v181, v181, v174
	v_mul_f32_e32 v102, v102, v180
	v_mul_f32_e32 v103, v103, v181
	v_lshlrev_b32_e32 v178, 16, v171
	v_and_b32_e32 v171, 0xffff0000, v171
	v_lshlrev_b32_e32 v179, 16, v175
	v_and_b32_e32 v175, 0xffff0000, v175
	v_mul_f32_e32 v104, 0xbfb8aa3b, v104
	v_mul_f32_e32 v105, 0xbfb8aa3b, v105
	v_mul_f32_e32 v180, 0xbfb8aa3b, v179
	v_mul_f32_e32 v181, 0xbfb8aa3b, v175
	v_exp_f32_e32 v104, v104
	v_exp_f32_e32 v105, v105
	v_exp_f32_e32 v180, v180
	v_exp_f32_e32 v181, v181
	v_add_f32_e32 v104, 1.0, v104
	v_add_f32_e32 v105, 1.0, v105
	v_add_f32_e32 v180, 1.0, v180
	v_add_f32_e32 v181, 1.0, v181
	v_rcp_f32_e32 v104, v104
	v_rcp_f32_e32 v105, v105
	v_rcp_f32_e32 v180, v180
	v_rcp_f32_e32 v181, v181
	v_mul_f32_e32 v104, v104, v178
	v_mul_f32_e32 v105, v105, v171
	v_mul_f32_e32 v180, v180, v179
	v_mul_f32_e32 v181, v181, v175
	v_mul_f32_e32 v104, v104, v180
	v_mul_f32_e32 v105, v105, v181
	v_lshlrev_b32_e32 v178, 16, v172
	v_and_b32_e32 v172, 0xffff0000, v172
	v_lshlrev_b32_e32 v179, 16, v176
	v_and_b32_e32 v176, 0xffff0000, v176
	v_mul_f32_e32 v98, 0xbfb8aa3b, v98
	v_mul_f32_e32 v99, 0xbfb8aa3b, v99
	v_mul_f32_e32 v180, 0xbfb8aa3b, v179
	v_mul_f32_e32 v181, 0xbfb8aa3b, v176
	v_exp_f32_e32 v98, v98
	v_exp_f32_e32 v99, v99
	v_exp_f32_e32 v180, v180
	v_exp_f32_e32 v181, v181
	v_add_f32_e32 v98, 1.0, v98
	v_add_f32_e32 v99, 1.0, v99
	v_add_f32_e32 v180, 1.0, v180
	v_add_f32_e32 v181, 1.0, v181
	v_rcp_f32_e32 v98, v98
	v_rcp_f32_e32 v99, v99
	v_rcp_f32_e32 v180, v180
	v_rcp_f32_e32 v181, v181
	v_mul_f32_e32 v98, v98, v178
	v_mul_f32_e32 v99, v99, v172
	v_mul_f32_e32 v180, v180, v179
	v_mul_f32_e32 v181, v181, v176
	v_mul_f32_e32 v98, v98, v180
	v_mul_f32_e32 v99, v99, v181
	v_lshlrev_b32_e32 v178, 16, v173
	v_and_b32_e32 v173, 0xffff0000, v173
	v_lshlrev_b32_e32 v179, 16, v177
	v_and_b32_e32 v177, 0xffff0000, v177
	v_mul_f32_e32 v100, 0xbfb8aa3b, v100
	v_mul_f32_e32 v101, 0xbfb8aa3b, v101
	v_mul_f32_e32 v180, 0xbfb8aa3b, v179
	v_mul_f32_e32 v181, 0xbfb8aa3b, v177
	v_exp_f32_e32 v100, v100
	v_exp_f32_e32 v101, v101
	v_exp_f32_e32 v180, v180
	v_exp_f32_e32 v181, v181
	v_add_f32_e32 v100, 1.0, v100
	v_add_f32_e32 v101, 1.0, v101
	v_add_f32_e32 v180, 1.0, v180
	v_add_f32_e32 v181, 1.0, v181
	v_rcp_f32_e32 v100, v100
	v_rcp_f32_e32 v101, v101
	v_rcp_f32_e32 v180, v180
	v_rcp_f32_e32 v181, v181
	v_mul_f32_e32 v100, v100, v178
	v_mul_f32_e32 v101, v101, v173
	v_mul_f32_e32 v180, v180, v179
	v_mul_f32_e32 v181, v181, v177
	v_mul_f32_e32 v100, v100, v180
	v_mul_f32_e32 v101, v101, v181
	v_cvt_pk_bf16_f32 v102, v102, v103
	v_cvt_pk_bf16_f32 v103, v104, v105
	v_cvt_pk_bf16_f32 v104, v98, v99
	v_cvt_pk_bf16_f32 v105, v100, v101
	global_store_dwordx4 v[146:147], v[102:105], off offset:256
	s_mov_b64 s[58:59], 0x20000
	v_lshl_add_u64 v[146:147], v[146:147], 0, s[58:59]
	s_mov_b64 s[58:59], 0x8000
	v_lshl_add_u64 v[142:143], v[142:143], 0, s[58:59]
	s_mov_b64 s[58:59], 0x4000
	v_lshl_add_u64 v[144:145], v[144:145], 0, s[58:59]
	global_load_dwordx4 v[170:173], v[142:143], off
	global_load_dwordx4 v[174:177], v[144:145], off
	s_waitcnt vmcnt(6)
	v_lshlrev_b32_e32 v178, 16, v154
	v_and_b32_e32 v154, 0xffff0000, v154
	v_lshlrev_b32_e32 v179, 16, v158
	v_and_b32_e32 v158, 0xffff0000, v158
	v_mul_f32_e32 v94, 0xbfb8aa3b, v94
	v_mul_f32_e32 v95, 0xbfb8aa3b, v95
	v_mul_f32_e32 v180, 0xbfb8aa3b, v179
	v_mul_f32_e32 v181, 0xbfb8aa3b, v158
	v_exp_f32_e32 v94, v94
	v_exp_f32_e32 v95, v95
	v_exp_f32_e32 v180, v180
	v_exp_f32_e32 v181, v181
	v_add_f32_e32 v94, 1.0, v94
	v_add_f32_e32 v95, 1.0, v95
	v_add_f32_e32 v180, 1.0, v180
	v_add_f32_e32 v181, 1.0, v181
	v_rcp_f32_e32 v94, v94
	v_rcp_f32_e32 v95, v95
	v_rcp_f32_e32 v180, v180
	v_rcp_f32_e32 v181, v181
	v_mul_f32_e32 v94, v94, v178
	v_mul_f32_e32 v95, v95, v154
	v_mul_f32_e32 v180, v180, v179
	v_mul_f32_e32 v181, v181, v158
	v_mul_f32_e32 v94, v94, v180
	v_mul_f32_e32 v95, v95, v181
	v_lshlrev_b32_e32 v178, 16, v155
	v_and_b32_e32 v155, 0xffff0000, v155
	v_lshlrev_b32_e32 v179, 16, v159
	v_and_b32_e32 v159, 0xffff0000, v159
	v_mul_f32_e32 v96, 0xbfb8aa3b, v96
	v_mul_f32_e32 v97, 0xbfb8aa3b, v97
	v_mul_f32_e32 v180, 0xbfb8aa3b, v179
	v_mul_f32_e32 v181, 0xbfb8aa3b, v159
	v_exp_f32_e32 v96, v96
	v_exp_f32_e32 v97, v97
	v_exp_f32_e32 v180, v180
	v_exp_f32_e32 v181, v181
	v_add_f32_e32 v96, 1.0, v96
	v_add_f32_e32 v97, 1.0, v97
	v_add_f32_e32 v180, 1.0, v180
	v_add_f32_e32 v181, 1.0, v181
	v_rcp_f32_e32 v96, v96
	v_rcp_f32_e32 v97, v97
	v_rcp_f32_e32 v180, v180
	v_rcp_f32_e32 v181, v181
	v_mul_f32_e32 v96, v96, v178
	v_mul_f32_e32 v97, v97, v155
	v_mul_f32_e32 v180, v180, v179
	v_mul_f32_e32 v181, v181, v159
	v_mul_f32_e32 v96, v96, v180
	v_mul_f32_e32 v97, v97, v181
	v_lshlrev_b32_e32 v178, 16, v156
	v_and_b32_e32 v156, 0xffff0000, v156
	v_lshlrev_b32_e32 v179, 16, v160
	v_and_b32_e32 v160, 0xffff0000, v160
	v_mul_f32_e32 v90, 0xbfb8aa3b, v90
	v_mul_f32_e32 v91, 0xbfb8aa3b, v91
	v_mul_f32_e32 v180, 0xbfb8aa3b, v179
	v_mul_f32_e32 v181, 0xbfb8aa3b, v160
	v_exp_f32_e32 v90, v90
	v_exp_f32_e32 v91, v91
	v_exp_f32_e32 v180, v180
	v_exp_f32_e32 v181, v181
	v_add_f32_e32 v90, 1.0, v90
	v_add_f32_e32 v91, 1.0, v91
	v_add_f32_e32 v180, 1.0, v180
	v_add_f32_e32 v181, 1.0, v181
	v_rcp_f32_e32 v90, v90
	v_rcp_f32_e32 v91, v91
	v_rcp_f32_e32 v180, v180
	v_rcp_f32_e32 v181, v181
	v_mul_f32_e32 v90, v90, v178
	v_mul_f32_e32 v91, v91, v156
	v_mul_f32_e32 v180, v180, v179
	v_mul_f32_e32 v181, v181, v160
	v_mul_f32_e32 v90, v90, v180
	v_mul_f32_e32 v91, v91, v181
	v_lshlrev_b32_e32 v178, 16, v157
	v_and_b32_e32 v157, 0xffff0000, v157
	v_lshlrev_b32_e32 v179, 16, v161
	v_and_b32_e32 v161, 0xffff0000, v161
	v_mul_f32_e32 v92, 0xbfb8aa3b, v92
	v_mul_f32_e32 v93, 0xbfb8aa3b, v93
	v_mul_f32_e32 v180, 0xbfb8aa3b, v179
	v_mul_f32_e32 v181, 0xbfb8aa3b, v161
	v_exp_f32_e32 v92, v92
	v_exp_f32_e32 v93, v93
	v_exp_f32_e32 v180, v180
	v_exp_f32_e32 v181, v181
	v_add_f32_e32 v92, 1.0, v92
	v_add_f32_e32 v93, 1.0, v93
	v_add_f32_e32 v180, 1.0, v180
	v_add_f32_e32 v181, 1.0, v181
	v_rcp_f32_e32 v92, v92
	v_rcp_f32_e32 v93, v93
	v_rcp_f32_e32 v180, v180
	v_rcp_f32_e32 v181, v181
	v_mul_f32_e32 v92, v92, v178
	v_mul_f32_e32 v93, v93, v157
	v_mul_f32_e32 v180, v180, v179
	v_mul_f32_e32 v181, v181, v161
	v_mul_f32_e32 v92, v92, v180
	v_mul_f32_e32 v93, v93, v181
	v_cvt_pk_bf16_f32 v94, v94, v95
	v_cvt_pk_bf16_f32 v95, v96, v97
	v_cvt_pk_bf16_f32 v96, v90, v91
	v_cvt_pk_bf16_f32 v97, v92, v93
	global_store_dwordx4 v[146:147], v[94:97], off
	global_load_dwordx4 v[154:157], v[142:143], off offset:256
	global_load_dwordx4 v[158:161], v[144:145], off offset:256
	s_waitcnt vmcnt(6)
	v_lshlrev_b32_e32 v178, 16, v162
	v_and_b32_e32 v162, 0xffff0000, v162
	v_lshlrev_b32_e32 v179, 16, v166
	v_and_b32_e32 v166, 0xffff0000, v166
	v_mul_f32_e32 v86, 0xbfb8aa3b, v86
	v_mul_f32_e32 v87, 0xbfb8aa3b, v87
	v_mul_f32_e32 v180, 0xbfb8aa3b, v179
	v_mul_f32_e32 v181, 0xbfb8aa3b, v166
	v_exp_f32_e32 v86, v86
	v_exp_f32_e32 v87, v87
	v_exp_f32_e32 v180, v180
	v_exp_f32_e32 v181, v181
	v_add_f32_e32 v86, 1.0, v86
	v_add_f32_e32 v87, 1.0, v87
	v_add_f32_e32 v180, 1.0, v180
	v_add_f32_e32 v181, 1.0, v181
	v_rcp_f32_e32 v86, v86
	v_rcp_f32_e32 v87, v87
	v_rcp_f32_e32 v180, v180
	v_rcp_f32_e32 v181, v181
	v_mul_f32_e32 v86, v86, v178
	v_mul_f32_e32 v87, v87, v162
	v_mul_f32_e32 v180, v180, v179
	v_mul_f32_e32 v181, v181, v166
	v_mul_f32_e32 v86, v86, v180
	v_mul_f32_e32 v87, v87, v181
	v_lshlrev_b32_e32 v178, 16, v163
	v_and_b32_e32 v163, 0xffff0000, v163
	v_lshlrev_b32_e32 v179, 16, v167
	v_and_b32_e32 v167, 0xffff0000, v167
	v_mul_f32_e32 v88, 0xbfb8aa3b, v88
	v_mul_f32_e32 v89, 0xbfb8aa3b, v89
	v_mul_f32_e32 v180, 0xbfb8aa3b, v179
	v_mul_f32_e32 v181, 0xbfb8aa3b, v167
	v_exp_f32_e32 v88, v88
	v_exp_f32_e32 v89, v89
	v_exp_f32_e32 v180, v180
	v_exp_f32_e32 v181, v181
	v_add_f32_e32 v88, 1.0, v88
	v_add_f32_e32 v89, 1.0, v89
	v_add_f32_e32 v180, 1.0, v180
	v_add_f32_e32 v181, 1.0, v181
	v_rcp_f32_e32 v88, v88
	v_rcp_f32_e32 v89, v89
	v_rcp_f32_e32 v180, v180
	v_rcp_f32_e32 v181, v181
	v_mul_f32_e32 v88, v88, v178
	v_mul_f32_e32 v89, v89, v163
	v_mul_f32_e32 v180, v180, v179
	v_mul_f32_e32 v181, v181, v167
	v_mul_f32_e32 v88, v88, v180
	v_mul_f32_e32 v89, v89, v181
	v_lshlrev_b32_e32 v178, 16, v164
	v_and_b32_e32 v164, 0xffff0000, v164
	v_lshlrev_b32_e32 v179, 16, v168
	v_and_b32_e32 v168, 0xffff0000, v168
	v_mul_f32_e32 v82, 0xbfb8aa3b, v82
	v_mul_f32_e32 v83, 0xbfb8aa3b, v83
	v_mul_f32_e32 v180, 0xbfb8aa3b, v179
	v_mul_f32_e32 v181, 0xbfb8aa3b, v168
	v_exp_f32_e32 v82, v82
	v_exp_f32_e32 v83, v83
	v_exp_f32_e32 v180, v180
	v_exp_f32_e32 v181, v181
	v_add_f32_e32 v82, 1.0, v82
	v_add_f32_e32 v83, 1.0, v83
	v_add_f32_e32 v180, 1.0, v180
	v_add_f32_e32 v181, 1.0, v181
	v_rcp_f32_e32 v82, v82
	v_rcp_f32_e32 v83, v83
	v_rcp_f32_e32 v180, v180
	v_rcp_f32_e32 v181, v181
	v_mul_f32_e32 v82, v82, v178
	v_mul_f32_e32 v83, v83, v164
	v_mul_f32_e32 v180, v180, v179
	v_mul_f32_e32 v181, v181, v168
	v_mul_f32_e32 v82, v82, v180
	v_mul_f32_e32 v83, v83, v181
	v_lshlrev_b32_e32 v178, 16, v165
	v_and_b32_e32 v165, 0xffff0000, v165
	v_lshlrev_b32_e32 v179, 16, v169
	v_and_b32_e32 v169, 0xffff0000, v169
	v_mul_f32_e32 v84, 0xbfb8aa3b, v84
	v_mul_f32_e32 v85, 0xbfb8aa3b, v85
	v_mul_f32_e32 v180, 0xbfb8aa3b, v179
	v_mul_f32_e32 v181, 0xbfb8aa3b, v169
	v_exp_f32_e32 v84, v84
	v_exp_f32_e32 v85, v85
	v_exp_f32_e32 v180, v180
	v_exp_f32_e32 v181, v181
	v_add_f32_e32 v84, 1.0, v84
	v_add_f32_e32 v85, 1.0, v85
	v_add_f32_e32 v180, 1.0, v180
	v_add_f32_e32 v181, 1.0, v181
	v_rcp_f32_e32 v84, v84
	v_rcp_f32_e32 v85, v85
	v_rcp_f32_e32 v180, v180
	v_rcp_f32_e32 v181, v181
	v_mul_f32_e32 v84, v84, v178
	v_mul_f32_e32 v85, v85, v165
	v_mul_f32_e32 v180, v180, v179
	v_mul_f32_e32 v181, v181, v169
	v_mul_f32_e32 v84, v84, v180
	v_mul_f32_e32 v85, v85, v181
	v_cvt_pk_bf16_f32 v86, v86, v87
	v_cvt_pk_bf16_f32 v87, v88, v89
	v_cvt_pk_bf16_f32 v88, v82, v83
	v_cvt_pk_bf16_f32 v89, v84, v85
	global_store_dwordx4 v[146:147], v[86:89], off offset:256
	s_mov_b64 s[58:59], 0x20000
	v_lshl_add_u64 v[146:147], v[146:147], 0, s[58:59]
	s_mov_b64 s[58:59], 0x28000
	v_lshl_add_u64 v[142:143], v[142:143], 0, s[58:59]
	s_mov_b64 s[58:59], 0x14000
	v_lshl_add_u64 v[144:145], v[144:145], 0, s[58:59]
	global_load_dwordx4 v[162:165], v[142:143], off
	global_load_dwordx4 v[166:169], v[144:145], off
	s_waitcnt vmcnt(6)
	v_lshlrev_b32_e32 v178, 16, v170
	v_and_b32_e32 v170, 0xffff0000, v170
	v_lshlrev_b32_e32 v179, 16, v174
	v_and_b32_e32 v174, 0xffff0000, v174
	v_mul_f32_e32 v78, 0xbfb8aa3b, v78
	v_mul_f32_e32 v79, 0xbfb8aa3b, v79
	v_mul_f32_e32 v180, 0xbfb8aa3b, v179
	v_mul_f32_e32 v181, 0xbfb8aa3b, v174
	v_exp_f32_e32 v78, v78
	v_exp_f32_e32 v79, v79
	v_exp_f32_e32 v180, v180
	v_exp_f32_e32 v181, v181
	v_add_f32_e32 v78, 1.0, v78
	v_add_f32_e32 v79, 1.0, v79
	v_add_f32_e32 v180, 1.0, v180
	v_add_f32_e32 v181, 1.0, v181
	v_rcp_f32_e32 v78, v78
	v_rcp_f32_e32 v79, v79
	v_rcp_f32_e32 v180, v180
	v_rcp_f32_e32 v181, v181
	v_mul_f32_e32 v78, v78, v178
	v_mul_f32_e32 v79, v79, v170
	v_mul_f32_e32 v180, v180, v179
	v_mul_f32_e32 v181, v181, v174
	v_mul_f32_e32 v78, v78, v180
	v_mul_f32_e32 v79, v79, v181
	v_lshlrev_b32_e32 v178, 16, v171
	v_and_b32_e32 v171, 0xffff0000, v171
	v_lshlrev_b32_e32 v179, 16, v175
	v_and_b32_e32 v175, 0xffff0000, v175
	v_mul_f32_e32 v80, 0xbfb8aa3b, v80
	v_mul_f32_e32 v81, 0xbfb8aa3b, v81
	v_mul_f32_e32 v180, 0xbfb8aa3b, v179
	v_mul_f32_e32 v181, 0xbfb8aa3b, v175
	v_exp_f32_e32 v80, v80
	v_exp_f32_e32 v81, v81
	v_exp_f32_e32 v180, v180
	v_exp_f32_e32 v181, v181
	v_add_f32_e32 v80, 1.0, v80
	v_add_f32_e32 v81, 1.0, v81
	v_add_f32_e32 v180, 1.0, v180
	v_add_f32_e32 v181, 1.0, v181
	v_rcp_f32_e32 v80, v80
	v_rcp_f32_e32 v81, v81
	v_rcp_f32_e32 v180, v180
	v_rcp_f32_e32 v181, v181
	v_mul_f32_e32 v80, v80, v178
	v_mul_f32_e32 v81, v81, v171
	v_mul_f32_e32 v180, v180, v179
	v_mul_f32_e32 v181, v181, v175
	v_mul_f32_e32 v80, v80, v180
	v_mul_f32_e32 v81, v81, v181
	v_lshlrev_b32_e32 v178, 16, v172
	v_and_b32_e32 v172, 0xffff0000, v172
	v_lshlrev_b32_e32 v179, 16, v176
	v_and_b32_e32 v176, 0xffff0000, v176
	v_mul_f32_e32 v74, 0xbfb8aa3b, v74
	v_mul_f32_e32 v75, 0xbfb8aa3b, v75
	v_mul_f32_e32 v180, 0xbfb8aa3b, v179
	v_mul_f32_e32 v181, 0xbfb8aa3b, v176
	v_exp_f32_e32 v74, v74
	v_exp_f32_e32 v75, v75
	v_exp_f32_e32 v180, v180
	v_exp_f32_e32 v181, v181
	v_add_f32_e32 v74, 1.0, v74
	v_add_f32_e32 v75, 1.0, v75
	v_add_f32_e32 v180, 1.0, v180
	v_add_f32_e32 v181, 1.0, v181
	v_rcp_f32_e32 v74, v74
	v_rcp_f32_e32 v75, v75
	v_rcp_f32_e32 v180, v180
	v_rcp_f32_e32 v181, v181
	v_mul_f32_e32 v74, v74, v178
	v_mul_f32_e32 v75, v75, v172
	v_mul_f32_e32 v180, v180, v179
	v_mul_f32_e32 v181, v181, v176
	v_mul_f32_e32 v74, v74, v180
	v_mul_f32_e32 v75, v75, v181
	v_lshlrev_b32_e32 v178, 16, v173
	v_and_b32_e32 v173, 0xffff0000, v173
	v_lshlrev_b32_e32 v179, 16, v177
	v_and_b32_e32 v177, 0xffff0000, v177
	v_mul_f32_e32 v76, 0xbfb8aa3b, v76
	v_mul_f32_e32 v77, 0xbfb8aa3b, v77
	v_mul_f32_e32 v180, 0xbfb8aa3b, v179
	v_mul_f32_e32 v181, 0xbfb8aa3b, v177
	v_exp_f32_e32 v76, v76
	v_exp_f32_e32 v77, v77
	v_exp_f32_e32 v180, v180
	v_exp_f32_e32 v181, v181
	v_add_f32_e32 v76, 1.0, v76
	v_add_f32_e32 v77, 1.0, v77
	v_add_f32_e32 v180, 1.0, v180
	v_add_f32_e32 v181, 1.0, v181
	v_rcp_f32_e32 v76, v76
	v_rcp_f32_e32 v77, v77
	v_rcp_f32_e32 v180, v180
	v_rcp_f32_e32 v181, v181
	v_mul_f32_e32 v76, v76, v178
	v_mul_f32_e32 v77, v77, v173
	v_mul_f32_e32 v180, v180, v179
	v_mul_f32_e32 v181, v181, v177
	v_mul_f32_e32 v76, v76, v180
	v_mul_f32_e32 v77, v77, v181
	v_cvt_pk_bf16_f32 v78, v78, v79
	v_cvt_pk_bf16_f32 v79, v80, v81
	v_cvt_pk_bf16_f32 v80, v74, v75
	v_cvt_pk_bf16_f32 v81, v76, v77
	global_store_dwordx4 v[146:147], v[78:81], off
	global_load_dwordx4 v[170:173], v[142:143], off offset:256
	global_load_dwordx4 v[174:177], v[144:145], off offset:256
	s_waitcnt vmcnt(6)
	v_lshlrev_b32_e32 v178, 16, v154
	v_and_b32_e32 v154, 0xffff0000, v154
	v_lshlrev_b32_e32 v179, 16, v158
	v_and_b32_e32 v158, 0xffff0000, v158
	v_mul_f32_e32 v70, 0xbfb8aa3b, v70
	v_mul_f32_e32 v71, 0xbfb8aa3b, v71
	v_mul_f32_e32 v180, 0xbfb8aa3b, v179
	v_mul_f32_e32 v181, 0xbfb8aa3b, v158
	v_exp_f32_e32 v70, v70
	v_exp_f32_e32 v71, v71
	v_exp_f32_e32 v180, v180
	v_exp_f32_e32 v181, v181
	v_add_f32_e32 v70, 1.0, v70
	v_add_f32_e32 v71, 1.0, v71
	v_add_f32_e32 v180, 1.0, v180
	v_add_f32_e32 v181, 1.0, v181
	v_rcp_f32_e32 v70, v70
	v_rcp_f32_e32 v71, v71
	v_rcp_f32_e32 v180, v180
	v_rcp_f32_e32 v181, v181
	v_mul_f32_e32 v70, v70, v178
	v_mul_f32_e32 v71, v71, v154
	v_mul_f32_e32 v180, v180, v179
	v_mul_f32_e32 v181, v181, v158
	v_mul_f32_e32 v70, v70, v180
	v_mul_f32_e32 v71, v71, v181
	v_lshlrev_b32_e32 v178, 16, v155
	v_and_b32_e32 v155, 0xffff0000, v155
	v_lshlrev_b32_e32 v179, 16, v159
	v_and_b32_e32 v159, 0xffff0000, v159
	v_mul_f32_e32 v72, 0xbfb8aa3b, v72
	v_mul_f32_e32 v73, 0xbfb8aa3b, v73
	v_mul_f32_e32 v180, 0xbfb8aa3b, v179
	v_mul_f32_e32 v181, 0xbfb8aa3b, v159
	v_exp_f32_e32 v72, v72
	v_exp_f32_e32 v73, v73
	v_exp_f32_e32 v180, v180
	v_exp_f32_e32 v181, v181
	v_add_f32_e32 v72, 1.0, v72
	v_add_f32_e32 v73, 1.0, v73
	v_add_f32_e32 v180, 1.0, v180
	v_add_f32_e32 v181, 1.0, v181
	v_rcp_f32_e32 v72, v72
	v_rcp_f32_e32 v73, v73
	v_rcp_f32_e32 v180, v180
	v_rcp_f32_e32 v181, v181
	v_mul_f32_e32 v72, v72, v178
	v_mul_f32_e32 v73, v73, v155
	v_mul_f32_e32 v180, v180, v179
	v_mul_f32_e32 v181, v181, v159
	v_mul_f32_e32 v72, v72, v180
	v_mul_f32_e32 v73, v73, v181
	v_lshlrev_b32_e32 v178, 16, v156
	v_and_b32_e32 v156, 0xffff0000, v156
	v_lshlrev_b32_e32 v179, 16, v160
	v_and_b32_e32 v160, 0xffff0000, v160
	v_mul_f32_e32 v66, 0xbfb8aa3b, v66
	v_mul_f32_e32 v67, 0xbfb8aa3b, v67
	v_mul_f32_e32 v180, 0xbfb8aa3b, v179
	v_mul_f32_e32 v181, 0xbfb8aa3b, v160
	v_exp_f32_e32 v66, v66
	v_exp_f32_e32 v67, v67
	v_exp_f32_e32 v180, v180
	v_exp_f32_e32 v181, v181
	v_add_f32_e32 v66, 1.0, v66
	v_add_f32_e32 v67, 1.0, v67
	v_add_f32_e32 v180, 1.0, v180
	v_add_f32_e32 v181, 1.0, v181
	v_rcp_f32_e32 v66, v66
	v_rcp_f32_e32 v67, v67
	v_rcp_f32_e32 v180, v180
	v_rcp_f32_e32 v181, v181
	v_mul_f32_e32 v66, v66, v178
	v_mul_f32_e32 v67, v67, v156
	v_mul_f32_e32 v180, v180, v179
	v_mul_f32_e32 v181, v181, v160
	v_mul_f32_e32 v66, v66, v180
	v_mul_f32_e32 v67, v67, v181
	v_lshlrev_b32_e32 v178, 16, v157
	v_and_b32_e32 v157, 0xffff0000, v157
	v_lshlrev_b32_e32 v179, 16, v161
	v_and_b32_e32 v161, 0xffff0000, v161
	v_mul_f32_e32 v68, 0xbfb8aa3b, v68
	v_mul_f32_e32 v69, 0xbfb8aa3b, v69
	v_mul_f32_e32 v180, 0xbfb8aa3b, v179
	v_mul_f32_e32 v181, 0xbfb8aa3b, v161
	v_exp_f32_e32 v68, v68
	v_exp_f32_e32 v69, v69
	v_exp_f32_e32 v180, v180
	v_exp_f32_e32 v181, v181
	v_add_f32_e32 v68, 1.0, v68
	v_add_f32_e32 v69, 1.0, v69
	v_add_f32_e32 v180, 1.0, v180
	v_add_f32_e32 v181, 1.0, v181
	v_rcp_f32_e32 v68, v68
	v_rcp_f32_e32 v69, v69
	v_rcp_f32_e32 v180, v180
	v_rcp_f32_e32 v181, v181
	v_mul_f32_e32 v68, v68, v178
	v_mul_f32_e32 v69, v69, v157
	v_mul_f32_e32 v180, v180, v179
	v_mul_f32_e32 v181, v181, v161
	v_mul_f32_e32 v68, v68, v180
	v_mul_f32_e32 v69, v69, v181
	v_cvt_pk_bf16_f32 v70, v70, v71
	v_cvt_pk_bf16_f32 v71, v72, v73
	v_cvt_pk_bf16_f32 v72, v66, v67
	v_cvt_pk_bf16_f32 v73, v68, v69
	global_store_dwordx4 v[146:147], v[70:73], off offset:256
	s_mov_b64 s[58:59], 0xa0000
	v_lshl_add_u64 v[146:147], v[146:147], 0, s[58:59]
	s_mov_b64 s[58:59], 0x8000
	v_lshl_add_u64 v[142:143], v[142:143], 0, s[58:59]
	s_mov_b64 s[58:59], 0x4000
	v_lshl_add_u64 v[144:145], v[144:145], 0, s[58:59]
	global_load_dwordx4 v[154:157], v[142:143], off
	global_load_dwordx4 v[158:161], v[144:145], off
	s_waitcnt vmcnt(6)
	v_lshlrev_b32_e32 v178, 16, v162
	v_and_b32_e32 v162, 0xffff0000, v162
	v_lshlrev_b32_e32 v179, 16, v166
	v_and_b32_e32 v166, 0xffff0000, v166
	v_mul_f32_e32 v62, 0xbfb8aa3b, v62
	v_mul_f32_e32 v63, 0xbfb8aa3b, v63
	v_mul_f32_e32 v180, 0xbfb8aa3b, v179
	v_mul_f32_e32 v181, 0xbfb8aa3b, v166
	v_exp_f32_e32 v62, v62
	v_exp_f32_e32 v63, v63
	v_exp_f32_e32 v180, v180
	v_exp_f32_e32 v181, v181
	v_add_f32_e32 v62, 1.0, v62
	v_add_f32_e32 v63, 1.0, v63
	v_add_f32_e32 v180, 1.0, v180
	v_add_f32_e32 v181, 1.0, v181
	v_rcp_f32_e32 v62, v62
	v_rcp_f32_e32 v63, v63
	v_rcp_f32_e32 v180, v180
	v_rcp_f32_e32 v181, v181
	v_mul_f32_e32 v62, v62, v178
	v_mul_f32_e32 v63, v63, v162
	v_mul_f32_e32 v180, v180, v179
	v_mul_f32_e32 v181, v181, v166
	v_mul_f32_e32 v62, v62, v180
	v_mul_f32_e32 v63, v63, v181
	v_lshlrev_b32_e32 v178, 16, v163
	v_and_b32_e32 v163, 0xffff0000, v163
	v_lshlrev_b32_e32 v179, 16, v167
	v_and_b32_e32 v167, 0xffff0000, v167
	v_mul_f32_e32 v64, 0xbfb8aa3b, v64
	v_mul_f32_e32 v65, 0xbfb8aa3b, v65
	v_mul_f32_e32 v180, 0xbfb8aa3b, v179
	v_mul_f32_e32 v181, 0xbfb8aa3b, v167
	v_exp_f32_e32 v64, v64
	v_exp_f32_e32 v65, v65
	v_exp_f32_e32 v180, v180
	v_exp_f32_e32 v181, v181
	v_add_f32_e32 v64, 1.0, v64
	v_add_f32_e32 v65, 1.0, v65
	v_add_f32_e32 v180, 1.0, v180
	v_add_f32_e32 v181, 1.0, v181
	v_rcp_f32_e32 v64, v64
	v_rcp_f32_e32 v65, v65
	v_rcp_f32_e32 v180, v180
	v_rcp_f32_e32 v181, v181
	v_mul_f32_e32 v64, v64, v178
	v_mul_f32_e32 v65, v65, v163
	v_mul_f32_e32 v180, v180, v179
	v_mul_f32_e32 v181, v181, v167
	v_mul_f32_e32 v64, v64, v180
	v_mul_f32_e32 v65, v65, v181
	v_lshlrev_b32_e32 v178, 16, v164
	v_and_b32_e32 v164, 0xffff0000, v164
	v_lshlrev_b32_e32 v179, 16, v168
	v_and_b32_e32 v168, 0xffff0000, v168
	v_mul_f32_e32 v58, 0xbfb8aa3b, v58
	v_mul_f32_e32 v59, 0xbfb8aa3b, v59
	v_mul_f32_e32 v180, 0xbfb8aa3b, v179
	v_mul_f32_e32 v181, 0xbfb8aa3b, v168
	v_exp_f32_e32 v58, v58
	v_exp_f32_e32 v59, v59
	v_exp_f32_e32 v180, v180
	v_exp_f32_e32 v181, v181
	v_add_f32_e32 v58, 1.0, v58
	v_add_f32_e32 v59, 1.0, v59
	v_add_f32_e32 v180, 1.0, v180
	v_add_f32_e32 v181, 1.0, v181
	v_rcp_f32_e32 v58, v58
	v_rcp_f32_e32 v59, v59
	v_rcp_f32_e32 v180, v180
	v_rcp_f32_e32 v181, v181
	v_mul_f32_e32 v58, v58, v178
	v_mul_f32_e32 v59, v59, v164
	v_mul_f32_e32 v180, v180, v179
	v_mul_f32_e32 v181, v181, v168
	v_mul_f32_e32 v58, v58, v180
	v_mul_f32_e32 v59, v59, v181
	v_lshlrev_b32_e32 v178, 16, v165
	v_and_b32_e32 v165, 0xffff0000, v165
	v_lshlrev_b32_e32 v179, 16, v169
	v_and_b32_e32 v169, 0xffff0000, v169
	v_mul_f32_e32 v60, 0xbfb8aa3b, v60
	v_mul_f32_e32 v61, 0xbfb8aa3b, v61
	v_mul_f32_e32 v180, 0xbfb8aa3b, v179
	v_mul_f32_e32 v181, 0xbfb8aa3b, v169
	v_exp_f32_e32 v60, v60
	v_exp_f32_e32 v61, v61
	v_exp_f32_e32 v180, v180
	v_exp_f32_e32 v181, v181
	v_add_f32_e32 v60, 1.0, v60
	v_add_f32_e32 v61, 1.0, v61
	v_add_f32_e32 v180, 1.0, v180
	v_add_f32_e32 v181, 1.0, v181
	v_rcp_f32_e32 v60, v60
	v_rcp_f32_e32 v61, v61
	v_rcp_f32_e32 v180, v180
	v_rcp_f32_e32 v181, v181
	v_mul_f32_e32 v60, v60, v178
	v_mul_f32_e32 v61, v61, v165
	v_mul_f32_e32 v180, v180, v179
	v_mul_f32_e32 v181, v181, v169
	v_mul_f32_e32 v60, v60, v180
	v_mul_f32_e32 v61, v61, v181
	v_cvt_pk_bf16_f32 v62, v62, v63
	v_cvt_pk_bf16_f32 v63, v64, v65
	v_cvt_pk_bf16_f32 v64, v58, v59
	v_cvt_pk_bf16_f32 v65, v60, v61
	global_store_dwordx4 v[146:147], v[62:65], off
	global_load_dwordx4 v[162:165], v[142:143], off offset:256
	global_load_dwordx4 v[166:169], v[144:145], off offset:256
	s_waitcnt vmcnt(6)
	v_lshlrev_b32_e32 v178, 16, v170
	v_and_b32_e32 v170, 0xffff0000, v170
	v_lshlrev_b32_e32 v179, 16, v174
	v_and_b32_e32 v174, 0xffff0000, v174
	v_mul_f32_e32 v54, 0xbfb8aa3b, v54
	v_mul_f32_e32 v55, 0xbfb8aa3b, v55
	v_mul_f32_e32 v180, 0xbfb8aa3b, v179
	v_mul_f32_e32 v181, 0xbfb8aa3b, v174
	v_exp_f32_e32 v54, v54
	v_exp_f32_e32 v55, v55
	v_exp_f32_e32 v180, v180
	v_exp_f32_e32 v181, v181
	v_add_f32_e32 v54, 1.0, v54
	v_add_f32_e32 v55, 1.0, v55
	v_add_f32_e32 v180, 1.0, v180
	v_add_f32_e32 v181, 1.0, v181
	v_rcp_f32_e32 v54, v54
	v_rcp_f32_e32 v55, v55
	v_rcp_f32_e32 v180, v180
	v_rcp_f32_e32 v181, v181
	v_mul_f32_e32 v54, v54, v178
	v_mul_f32_e32 v55, v55, v170
	v_mul_f32_e32 v180, v180, v179
	v_mul_f32_e32 v181, v181, v174
	v_mul_f32_e32 v54, v54, v180
	v_mul_f32_e32 v55, v55, v181
	v_lshlrev_b32_e32 v178, 16, v171
	v_and_b32_e32 v171, 0xffff0000, v171
	v_lshlrev_b32_e32 v179, 16, v175
	v_and_b32_e32 v175, 0xffff0000, v175
	v_mul_f32_e32 v56, 0xbfb8aa3b, v56
	v_mul_f32_e32 v57, 0xbfb8aa3b, v57
	v_mul_f32_e32 v180, 0xbfb8aa3b, v179
	v_mul_f32_e32 v181, 0xbfb8aa3b, v175
	v_exp_f32_e32 v56, v56
	v_exp_f32_e32 v57, v57
	v_exp_f32_e32 v180, v180
	v_exp_f32_e32 v181, v181
	v_add_f32_e32 v56, 1.0, v56
	v_add_f32_e32 v57, 1.0, v57
	v_add_f32_e32 v180, 1.0, v180
	v_add_f32_e32 v181, 1.0, v181
	v_rcp_f32_e32 v56, v56
	v_rcp_f32_e32 v57, v57
	v_rcp_f32_e32 v180, v180
	v_rcp_f32_e32 v181, v181
	v_mul_f32_e32 v56, v56, v178
	v_mul_f32_e32 v57, v57, v171
	v_mul_f32_e32 v180, v180, v179
	v_mul_f32_e32 v181, v181, v175
	v_mul_f32_e32 v56, v56, v180
	v_mul_f32_e32 v57, v57, v181
	v_lshlrev_b32_e32 v178, 16, v172
	v_and_b32_e32 v172, 0xffff0000, v172
	v_lshlrev_b32_e32 v179, 16, v176
	v_and_b32_e32 v176, 0xffff0000, v176
	v_mul_f32_e32 v50, 0xbfb8aa3b, v50
	v_mul_f32_e32 v51, 0xbfb8aa3b, v51
	v_mul_f32_e32 v180, 0xbfb8aa3b, v179
	v_mul_f32_e32 v181, 0xbfb8aa3b, v176
	v_exp_f32_e32 v50, v50
	v_exp_f32_e32 v51, v51
	v_exp_f32_e32 v180, v180
	v_exp_f32_e32 v181, v181
	v_add_f32_e32 v50, 1.0, v50
	v_add_f32_e32 v51, 1.0, v51
	v_add_f32_e32 v180, 1.0, v180
	v_add_f32_e32 v181, 1.0, v181
	v_rcp_f32_e32 v50, v50
	v_rcp_f32_e32 v51, v51
	v_rcp_f32_e32 v180, v180
	v_rcp_f32_e32 v181, v181
	v_mul_f32_e32 v50, v50, v178
	v_mul_f32_e32 v51, v51, v172
	v_mul_f32_e32 v180, v180, v179
	v_mul_f32_e32 v181, v181, v176
	v_mul_f32_e32 v50, v50, v180
	v_mul_f32_e32 v51, v51, v181
	v_lshlrev_b32_e32 v178, 16, v173
	v_and_b32_e32 v173, 0xffff0000, v173
	v_lshlrev_b32_e32 v179, 16, v177
	v_and_b32_e32 v177, 0xffff0000, v177
	v_mul_f32_e32 v52, 0xbfb8aa3b, v52
	v_mul_f32_e32 v53, 0xbfb8aa3b, v53
	v_mul_f32_e32 v180, 0xbfb8aa3b, v179
	v_mul_f32_e32 v181, 0xbfb8aa3b, v177
	v_exp_f32_e32 v52, v52
	v_exp_f32_e32 v53, v53
	v_exp_f32_e32 v180, v180
	v_exp_f32_e32 v181, v181
	v_add_f32_e32 v52, 1.0, v52
	v_add_f32_e32 v53, 1.0, v53
	v_add_f32_e32 v180, 1.0, v180
	v_add_f32_e32 v181, 1.0, v181
	v_rcp_f32_e32 v52, v52
	v_rcp_f32_e32 v53, v53
	v_rcp_f32_e32 v180, v180
	v_rcp_f32_e32 v181, v181
	v_mul_f32_e32 v52, v52, v178
	v_mul_f32_e32 v53, v53, v173
	v_mul_f32_e32 v180, v180, v179
	v_mul_f32_e32 v181, v181, v177
	v_mul_f32_e32 v52, v52, v180
	v_mul_f32_e32 v53, v53, v181
	v_cvt_pk_bf16_f32 v54, v54, v55
	v_cvt_pk_bf16_f32 v55, v56, v57
	v_cvt_pk_bf16_f32 v56, v50, v51
	v_cvt_pk_bf16_f32 v57, v52, v53
	global_store_dwordx4 v[146:147], v[54:57], off offset:256
	s_mov_b64 s[58:59], 0x20000
	v_lshl_add_u64 v[146:147], v[146:147], 0, s[58:59]
	s_mov_b64 s[58:59], 0x8000
	v_lshl_add_u64 v[142:143], v[142:143], 0, s[58:59]
	s_mov_b64 s[58:59], 0x4000
	v_lshl_add_u64 v[144:145], v[144:145], 0, s[58:59]
	global_load_dwordx4 v[170:173], v[142:143], off
	global_load_dwordx4 v[174:177], v[144:145], off
	s_waitcnt vmcnt(6)
	v_lshlrev_b32_e32 v178, 16, v154
	v_and_b32_e32 v154, 0xffff0000, v154
	v_lshlrev_b32_e32 v179, 16, v158
	v_and_b32_e32 v158, 0xffff0000, v158
	v_mul_f32_e32 v46, 0xbfb8aa3b, v46
	v_mul_f32_e32 v47, 0xbfb8aa3b, v47
	v_mul_f32_e32 v180, 0xbfb8aa3b, v179
	v_mul_f32_e32 v181, 0xbfb8aa3b, v158
	v_exp_f32_e32 v46, v46
	v_exp_f32_e32 v47, v47
	v_exp_f32_e32 v180, v180
	v_exp_f32_e32 v181, v181
	v_add_f32_e32 v46, 1.0, v46
	v_add_f32_e32 v47, 1.0, v47
	v_add_f32_e32 v180, 1.0, v180
	v_add_f32_e32 v181, 1.0, v181
	v_rcp_f32_e32 v46, v46
	v_rcp_f32_e32 v47, v47
	v_rcp_f32_e32 v180, v180
	v_rcp_f32_e32 v181, v181
	v_mul_f32_e32 v46, v46, v178
	v_mul_f32_e32 v47, v47, v154
	v_mul_f32_e32 v180, v180, v179
	v_mul_f32_e32 v181, v181, v158
	v_mul_f32_e32 v46, v46, v180
	v_mul_f32_e32 v47, v47, v181
	v_lshlrev_b32_e32 v178, 16, v155
	v_and_b32_e32 v155, 0xffff0000, v155
	v_lshlrev_b32_e32 v179, 16, v159
	v_and_b32_e32 v159, 0xffff0000, v159
	v_mul_f32_e32 v48, 0xbfb8aa3b, v48
	v_mul_f32_e32 v49, 0xbfb8aa3b, v49
	v_mul_f32_e32 v180, 0xbfb8aa3b, v179
	v_mul_f32_e32 v181, 0xbfb8aa3b, v159
	v_exp_f32_e32 v48, v48
	v_exp_f32_e32 v49, v49
	v_exp_f32_e32 v180, v180
	v_exp_f32_e32 v181, v181
	v_add_f32_e32 v48, 1.0, v48
	v_add_f32_e32 v49, 1.0, v49
	v_add_f32_e32 v180, 1.0, v180
	v_add_f32_e32 v181, 1.0, v181
	v_rcp_f32_e32 v48, v48
	v_rcp_f32_e32 v49, v49
	v_rcp_f32_e32 v180, v180
	v_rcp_f32_e32 v181, v181
	v_mul_f32_e32 v48, v48, v178
	v_mul_f32_e32 v49, v49, v155
	v_mul_f32_e32 v180, v180, v179
	v_mul_f32_e32 v181, v181, v159
	v_mul_f32_e32 v48, v48, v180
	v_mul_f32_e32 v49, v49, v181
	v_lshlrev_b32_e32 v178, 16, v156
	v_and_b32_e32 v156, 0xffff0000, v156
	v_lshlrev_b32_e32 v179, 16, v160
	v_and_b32_e32 v160, 0xffff0000, v160
	v_mul_f32_e32 v42, 0xbfb8aa3b, v42
	v_mul_f32_e32 v43, 0xbfb8aa3b, v43
	v_mul_f32_e32 v180, 0xbfb8aa3b, v179
	v_mul_f32_e32 v181, 0xbfb8aa3b, v160
	v_exp_f32_e32 v42, v42
	v_exp_f32_e32 v43, v43
	v_exp_f32_e32 v180, v180
	v_exp_f32_e32 v181, v181
	v_add_f32_e32 v42, 1.0, v42
	v_add_f32_e32 v43, 1.0, v43
	v_add_f32_e32 v180, 1.0, v180
	v_add_f32_e32 v181, 1.0, v181
	v_rcp_f32_e32 v42, v42
	v_rcp_f32_e32 v43, v43
	v_rcp_f32_e32 v180, v180
	v_rcp_f32_e32 v181, v181
	v_mul_f32_e32 v42, v42, v178
	v_mul_f32_e32 v43, v43, v156
	v_mul_f32_e32 v180, v180, v179
	v_mul_f32_e32 v181, v181, v160
	v_mul_f32_e32 v42, v42, v180
	v_mul_f32_e32 v43, v43, v181
	v_lshlrev_b32_e32 v178, 16, v157
	v_and_b32_e32 v157, 0xffff0000, v157
	v_lshlrev_b32_e32 v179, 16, v161
	v_and_b32_e32 v161, 0xffff0000, v161
	v_mul_f32_e32 v44, 0xbfb8aa3b, v44
	v_mul_f32_e32 v45, 0xbfb8aa3b, v45
	v_mul_f32_e32 v180, 0xbfb8aa3b, v179
	v_mul_f32_e32 v181, 0xbfb8aa3b, v161
	v_exp_f32_e32 v44, v44
	v_exp_f32_e32 v45, v45
	v_exp_f32_e32 v180, v180
	v_exp_f32_e32 v181, v181
	v_add_f32_e32 v44, 1.0, v44
	v_add_f32_e32 v45, 1.0, v45
	v_add_f32_e32 v180, 1.0, v180
	v_add_f32_e32 v181, 1.0, v181
	v_rcp_f32_e32 v44, v44
	v_rcp_f32_e32 v45, v45
	v_rcp_f32_e32 v180, v180
	v_rcp_f32_e32 v181, v181
	v_mul_f32_e32 v44, v44, v178
	v_mul_f32_e32 v45, v45, v157
	v_mul_f32_e32 v180, v180, v179
	v_mul_f32_e32 v181, v181, v161
	v_mul_f32_e32 v44, v44, v180
	v_mul_f32_e32 v45, v45, v181
	v_cvt_pk_bf16_f32 v46, v46, v47
	v_cvt_pk_bf16_f32 v47, v48, v49
	v_cvt_pk_bf16_f32 v48, v42, v43
	v_cvt_pk_bf16_f32 v49, v44, v45
	global_store_dwordx4 v[146:147], v[46:49], off
	global_load_dwordx4 v[154:157], v[142:143], off offset:256
	global_load_dwordx4 v[158:161], v[144:145], off offset:256
	s_waitcnt vmcnt(6)
	v_lshlrev_b32_e32 v178, 16, v162
	v_and_b32_e32 v162, 0xffff0000, v162
	v_lshlrev_b32_e32 v179, 16, v166
	v_and_b32_e32 v166, 0xffff0000, v166
	v_mul_f32_e32 v38, 0xbfb8aa3b, v38
	v_mul_f32_e32 v39, 0xbfb8aa3b, v39
	v_mul_f32_e32 v180, 0xbfb8aa3b, v179
	v_mul_f32_e32 v181, 0xbfb8aa3b, v166
	v_exp_f32_e32 v38, v38
	v_exp_f32_e32 v39, v39
	v_exp_f32_e32 v180, v180
	v_exp_f32_e32 v181, v181
	v_add_f32_e32 v38, 1.0, v38
	v_add_f32_e32 v39, 1.0, v39
	v_add_f32_e32 v180, 1.0, v180
	v_add_f32_e32 v181, 1.0, v181
	v_rcp_f32_e32 v38, v38
	v_rcp_f32_e32 v39, v39
	v_rcp_f32_e32 v180, v180
	v_rcp_f32_e32 v181, v181
	v_mul_f32_e32 v38, v38, v178
	v_mul_f32_e32 v39, v39, v162
	v_mul_f32_e32 v180, v180, v179
	v_mul_f32_e32 v181, v181, v166
	v_mul_f32_e32 v38, v38, v180
	v_mul_f32_e32 v39, v39, v181
	v_lshlrev_b32_e32 v178, 16, v163
	v_and_b32_e32 v163, 0xffff0000, v163
	v_lshlrev_b32_e32 v179, 16, v167
	v_and_b32_e32 v167, 0xffff0000, v167
	v_mul_f32_e32 v40, 0xbfb8aa3b, v40
	v_mul_f32_e32 v41, 0xbfb8aa3b, v41
	v_mul_f32_e32 v180, 0xbfb8aa3b, v179
	v_mul_f32_e32 v181, 0xbfb8aa3b, v167
	v_exp_f32_e32 v40, v40
	v_exp_f32_e32 v41, v41
	v_exp_f32_e32 v180, v180
	v_exp_f32_e32 v181, v181
	v_add_f32_e32 v40, 1.0, v40
	v_add_f32_e32 v41, 1.0, v41
	v_add_f32_e32 v180, 1.0, v180
	v_add_f32_e32 v181, 1.0, v181
	v_rcp_f32_e32 v40, v40
	v_rcp_f32_e32 v41, v41
	v_rcp_f32_e32 v180, v180
	v_rcp_f32_e32 v181, v181
	v_mul_f32_e32 v40, v40, v178
	v_mul_f32_e32 v41, v41, v163
	v_mul_f32_e32 v180, v180, v179
	v_mul_f32_e32 v181, v181, v167
	v_mul_f32_e32 v40, v40, v180
	v_mul_f32_e32 v41, v41, v181
	v_lshlrev_b32_e32 v178, 16, v164
	v_and_b32_e32 v164, 0xffff0000, v164
	v_lshlrev_b32_e32 v179, 16, v168
	v_and_b32_e32 v168, 0xffff0000, v168
	v_mul_f32_e32 v34, 0xbfb8aa3b, v34
	v_mul_f32_e32 v35, 0xbfb8aa3b, v35
	v_mul_f32_e32 v180, 0xbfb8aa3b, v179
	v_mul_f32_e32 v181, 0xbfb8aa3b, v168
	v_exp_f32_e32 v34, v34
	v_exp_f32_e32 v35, v35
	v_exp_f32_e32 v180, v180
	v_exp_f32_e32 v181, v181
	v_add_f32_e32 v34, 1.0, v34
	v_add_f32_e32 v35, 1.0, v35
	v_add_f32_e32 v180, 1.0, v180
	v_add_f32_e32 v181, 1.0, v181
	v_rcp_f32_e32 v34, v34
	v_rcp_f32_e32 v35, v35
	v_rcp_f32_e32 v180, v180
	v_rcp_f32_e32 v181, v181
	v_mul_f32_e32 v34, v34, v178
	v_mul_f32_e32 v35, v35, v164
	v_mul_f32_e32 v180, v180, v179
	v_mul_f32_e32 v181, v181, v168
	v_mul_f32_e32 v34, v34, v180
	v_mul_f32_e32 v35, v35, v181
	v_lshlrev_b32_e32 v178, 16, v165
	v_and_b32_e32 v165, 0xffff0000, v165
	v_lshlrev_b32_e32 v179, 16, v169
	v_and_b32_e32 v169, 0xffff0000, v169
	v_mul_f32_e32 v36, 0xbfb8aa3b, v36
	v_mul_f32_e32 v37, 0xbfb8aa3b, v37
	v_mul_f32_e32 v180, 0xbfb8aa3b, v179
	v_mul_f32_e32 v181, 0xbfb8aa3b, v169
	v_exp_f32_e32 v36, v36
	v_exp_f32_e32 v37, v37
	v_exp_f32_e32 v180, v180
	v_exp_f32_e32 v181, v181
	v_add_f32_e32 v36, 1.0, v36
	v_add_f32_e32 v37, 1.0, v37
	v_add_f32_e32 v180, 1.0, v180
	v_add_f32_e32 v181, 1.0, v181
	v_rcp_f32_e32 v36, v36
	v_rcp_f32_e32 v37, v37
	v_rcp_f32_e32 v180, v180
	v_rcp_f32_e32 v181, v181
	v_mul_f32_e32 v36, v36, v178
	v_mul_f32_e32 v37, v37, v165
	v_mul_f32_e32 v180, v180, v179
	v_mul_f32_e32 v181, v181, v169
	v_mul_f32_e32 v36, v36, v180
	v_mul_f32_e32 v37, v37, v181
	v_cvt_pk_bf16_f32 v38, v38, v39
	v_cvt_pk_bf16_f32 v39, v40, v41
	v_cvt_pk_bf16_f32 v40, v34, v35
	v_cvt_pk_bf16_f32 v41, v36, v37
	global_store_dwordx4 v[146:147], v[38:41], off offset:256
	s_mov_b64 s[58:59], 0x20000
	v_lshl_add_u64 v[146:147], v[146:147], 0, s[58:59]
	s_mov_b64 s[58:59], 0x8000
	v_lshl_add_u64 v[142:143], v[142:143], 0, s[58:59]
	s_mov_b64 s[58:59], 0x4000
	v_lshl_add_u64 v[144:145], v[144:145], 0, s[58:59]
	global_load_dwordx4 v[162:165], v[142:143], off
	global_load_dwordx4 v[166:169], v[144:145], off
	s_waitcnt vmcnt(6)
	v_lshlrev_b32_e32 v178, 16, v170
	v_and_b32_e32 v170, 0xffff0000, v170
	v_lshlrev_b32_e32 v179, 16, v174
	v_and_b32_e32 v174, 0xffff0000, v174
	v_mul_f32_e32 v30, 0xbfb8aa3b, v30
	v_mul_f32_e32 v31, 0xbfb8aa3b, v31
	v_mul_f32_e32 v180, 0xbfb8aa3b, v179
	v_mul_f32_e32 v181, 0xbfb8aa3b, v174
	v_exp_f32_e32 v30, v30
	v_exp_f32_e32 v31, v31
	v_exp_f32_e32 v180, v180
	v_exp_f32_e32 v181, v181
	v_add_f32_e32 v30, 1.0, v30
	v_add_f32_e32 v31, 1.0, v31
	v_add_f32_e32 v180, 1.0, v180
	v_add_f32_e32 v181, 1.0, v181
	v_rcp_f32_e32 v30, v30
	v_rcp_f32_e32 v31, v31
	v_rcp_f32_e32 v180, v180
	v_rcp_f32_e32 v181, v181
	v_mul_f32_e32 v30, v30, v178
	v_mul_f32_e32 v31, v31, v170
	v_mul_f32_e32 v180, v180, v179
	v_mul_f32_e32 v181, v181, v174
	v_mul_f32_e32 v30, v30, v180
	v_mul_f32_e32 v31, v31, v181
	v_lshlrev_b32_e32 v178, 16, v171
	v_and_b32_e32 v171, 0xffff0000, v171
	v_lshlrev_b32_e32 v179, 16, v175
	v_and_b32_e32 v175, 0xffff0000, v175
	v_mul_f32_e32 v32, 0xbfb8aa3b, v32
	v_mul_f32_e32 v33, 0xbfb8aa3b, v33
	v_mul_f32_e32 v180, 0xbfb8aa3b, v179
	v_mul_f32_e32 v181, 0xbfb8aa3b, v175
	v_exp_f32_e32 v32, v32
	v_exp_f32_e32 v33, v33
	v_exp_f32_e32 v180, v180
	v_exp_f32_e32 v181, v181
	v_add_f32_e32 v32, 1.0, v32
	v_add_f32_e32 v33, 1.0, v33
	v_add_f32_e32 v180, 1.0, v180
	v_add_f32_e32 v181, 1.0, v181
	v_rcp_f32_e32 v32, v32
	v_rcp_f32_e32 v33, v33
	v_rcp_f32_e32 v180, v180
	v_rcp_f32_e32 v181, v181
	v_mul_f32_e32 v32, v32, v178
	v_mul_f32_e32 v33, v33, v171
	v_mul_f32_e32 v180, v180, v179
	v_mul_f32_e32 v181, v181, v175
	v_mul_f32_e32 v32, v32, v180
	v_mul_f32_e32 v33, v33, v181
	v_lshlrev_b32_e32 v178, 16, v172
	v_and_b32_e32 v172, 0xffff0000, v172
	v_lshlrev_b32_e32 v179, 16, v176
	v_and_b32_e32 v176, 0xffff0000, v176
	v_mul_f32_e32 v26, 0xbfb8aa3b, v26
	v_mul_f32_e32 v27, 0xbfb8aa3b, v27
	v_mul_f32_e32 v180, 0xbfb8aa3b, v179
	v_mul_f32_e32 v181, 0xbfb8aa3b, v176
	v_exp_f32_e32 v26, v26
	v_exp_f32_e32 v27, v27
	v_exp_f32_e32 v180, v180
	v_exp_f32_e32 v181, v181
	v_add_f32_e32 v26, 1.0, v26
	v_add_f32_e32 v27, 1.0, v27
	v_add_f32_e32 v180, 1.0, v180
	v_add_f32_e32 v181, 1.0, v181
	v_rcp_f32_e32 v26, v26
	v_rcp_f32_e32 v27, v27
	v_rcp_f32_e32 v180, v180
	v_rcp_f32_e32 v181, v181
	v_mul_f32_e32 v26, v26, v178
	v_mul_f32_e32 v27, v27, v172
	v_mul_f32_e32 v180, v180, v179
	v_mul_f32_e32 v181, v181, v176
	v_mul_f32_e32 v26, v26, v180
	v_mul_f32_e32 v27, v27, v181
	v_lshlrev_b32_e32 v178, 16, v173
	v_and_b32_e32 v173, 0xffff0000, v173
	v_lshlrev_b32_e32 v179, 16, v177
	v_and_b32_e32 v177, 0xffff0000, v177
	v_mul_f32_e32 v28, 0xbfb8aa3b, v28
	v_mul_f32_e32 v29, 0xbfb8aa3b, v29
	v_mul_f32_e32 v180, 0xbfb8aa3b, v179
	v_mul_f32_e32 v181, 0xbfb8aa3b, v177
	v_exp_f32_e32 v28, v28
	v_exp_f32_e32 v29, v29
	v_exp_f32_e32 v180, v180
	v_exp_f32_e32 v181, v181
	v_add_f32_e32 v28, 1.0, v28
	v_add_f32_e32 v29, 1.0, v29
	v_add_f32_e32 v180, 1.0, v180
	v_add_f32_e32 v181, 1.0, v181
	v_rcp_f32_e32 v28, v28
	v_rcp_f32_e32 v29, v29
	v_rcp_f32_e32 v180, v180
	v_rcp_f32_e32 v181, v181
	v_mul_f32_e32 v28, v28, v178
	v_mul_f32_e32 v29, v29, v173
	v_mul_f32_e32 v180, v180, v179
	v_mul_f32_e32 v181, v181, v177
	v_mul_f32_e32 v28, v28, v180
	v_mul_f32_e32 v29, v29, v181
	v_cvt_pk_bf16_f32 v30, v30, v31
	v_cvt_pk_bf16_f32 v31, v32, v33
	v_cvt_pk_bf16_f32 v32, v26, v27
	v_cvt_pk_bf16_f32 v33, v28, v29
	global_store_dwordx4 v[146:147], v[30:33], off
	global_load_dwordx4 v[170:173], v[142:143], off offset:256
	global_load_dwordx4 v[174:177], v[144:145], off offset:256
	s_waitcnt vmcnt(6)
	v_lshlrev_b32_e32 v178, 16, v154
	v_and_b32_e32 v154, 0xffff0000, v154
	v_lshlrev_b32_e32 v179, 16, v158
	v_and_b32_e32 v158, 0xffff0000, v158
	v_mul_f32_e32 v22, 0xbfb8aa3b, v22
	v_mul_f32_e32 v23, 0xbfb8aa3b, v23
	v_mul_f32_e32 v180, 0xbfb8aa3b, v179
	v_mul_f32_e32 v181, 0xbfb8aa3b, v158
	v_exp_f32_e32 v22, v22
	v_exp_f32_e32 v23, v23
	v_exp_f32_e32 v180, v180
	v_exp_f32_e32 v181, v181
	v_add_f32_e32 v22, 1.0, v22
	v_add_f32_e32 v23, 1.0, v23
	v_add_f32_e32 v180, 1.0, v180
	v_add_f32_e32 v181, 1.0, v181
	v_rcp_f32_e32 v22, v22
	v_rcp_f32_e32 v23, v23
	v_rcp_f32_e32 v180, v180
	v_rcp_f32_e32 v181, v181
	v_mul_f32_e32 v22, v22, v178
	v_mul_f32_e32 v23, v23, v154
	v_mul_f32_e32 v180, v180, v179
	v_mul_f32_e32 v181, v181, v158
	v_mul_f32_e32 v22, v22, v180
	v_mul_f32_e32 v23, v23, v181
	v_lshlrev_b32_e32 v178, 16, v155
	v_and_b32_e32 v155, 0xffff0000, v155
	v_lshlrev_b32_e32 v179, 16, v159
	v_and_b32_e32 v159, 0xffff0000, v159
	v_mul_f32_e32 v24, 0xbfb8aa3b, v24
	v_mul_f32_e32 v25, 0xbfb8aa3b, v25
	v_mul_f32_e32 v180, 0xbfb8aa3b, v179
	v_mul_f32_e32 v181, 0xbfb8aa3b, v159
	v_exp_f32_e32 v24, v24
	v_exp_f32_e32 v25, v25
	v_exp_f32_e32 v180, v180
	v_exp_f32_e32 v181, v181
	v_add_f32_e32 v24, 1.0, v24
	v_add_f32_e32 v25, 1.0, v25
	v_add_f32_e32 v180, 1.0, v180
	v_add_f32_e32 v181, 1.0, v181
	v_rcp_f32_e32 v24, v24
	v_rcp_f32_e32 v25, v25
	v_rcp_f32_e32 v180, v180
	v_rcp_f32_e32 v181, v181
	v_mul_f32_e32 v24, v24, v178
	v_mul_f32_e32 v25, v25, v155
	v_mul_f32_e32 v180, v180, v179
	v_mul_f32_e32 v181, v181, v159
	v_mul_f32_e32 v24, v24, v180
	v_mul_f32_e32 v25, v25, v181
	v_lshlrev_b32_e32 v178, 16, v156
	v_and_b32_e32 v156, 0xffff0000, v156
	v_lshlrev_b32_e32 v179, 16, v160
	v_and_b32_e32 v160, 0xffff0000, v160
	v_mul_f32_e32 v18, 0xbfb8aa3b, v18
	v_mul_f32_e32 v19, 0xbfb8aa3b, v19
	v_mul_f32_e32 v180, 0xbfb8aa3b, v179
	v_mul_f32_e32 v181, 0xbfb8aa3b, v160
	v_exp_f32_e32 v18, v18
	v_exp_f32_e32 v19, v19
	v_exp_f32_e32 v180, v180
	v_exp_f32_e32 v181, v181
	v_add_f32_e32 v18, 1.0, v18
	v_add_f32_e32 v19, 1.0, v19
	v_add_f32_e32 v180, 1.0, v180
	v_add_f32_e32 v181, 1.0, v181
	v_rcp_f32_e32 v18, v18
	v_rcp_f32_e32 v19, v19
	v_rcp_f32_e32 v180, v180
	v_rcp_f32_e32 v181, v181
	v_mul_f32_e32 v18, v18, v178
	v_mul_f32_e32 v19, v19, v156
	v_mul_f32_e32 v180, v180, v179
	v_mul_f32_e32 v181, v181, v160
	v_mul_f32_e32 v18, v18, v180
	v_mul_f32_e32 v19, v19, v181
	v_lshlrev_b32_e32 v178, 16, v157
	v_and_b32_e32 v157, 0xffff0000, v157
	v_lshlrev_b32_e32 v179, 16, v161
	v_and_b32_e32 v161, 0xffff0000, v161
	v_mul_f32_e32 v20, 0xbfb8aa3b, v20
	v_mul_f32_e32 v21, 0xbfb8aa3b, v21
	v_mul_f32_e32 v180, 0xbfb8aa3b, v179
	v_mul_f32_e32 v181, 0xbfb8aa3b, v161
	v_exp_f32_e32 v20, v20
	v_exp_f32_e32 v21, v21
	v_exp_f32_e32 v180, v180
	v_exp_f32_e32 v181, v181
	v_add_f32_e32 v20, 1.0, v20
	v_add_f32_e32 v21, 1.0, v21
	v_add_f32_e32 v180, 1.0, v180
	v_add_f32_e32 v181, 1.0, v181
	v_rcp_f32_e32 v20, v20
	v_rcp_f32_e32 v21, v21
	v_rcp_f32_e32 v180, v180
	v_rcp_f32_e32 v181, v181
	v_mul_f32_e32 v20, v20, v178
	v_mul_f32_e32 v21, v21, v157
	v_mul_f32_e32 v180, v180, v179
	v_mul_f32_e32 v181, v181, v161
	v_mul_f32_e32 v20, v20, v180
	v_mul_f32_e32 v21, v21, v181
	v_cvt_pk_bf16_f32 v22, v22, v23
	v_cvt_pk_bf16_f32 v23, v24, v25
	v_cvt_pk_bf16_f32 v24, v18, v19
	v_cvt_pk_bf16_f32 v25, v20, v21
	global_store_dwordx4 v[146:147], v[22:25], off offset:256
	s_mov_b64 s[58:59], 0x20000
	v_lshl_add_u64 v[146:147], v[146:147], 0, s[58:59]
	s_waitcnt vmcnt(4)
	v_lshlrev_b32_e32 v178, 16, v162
	v_and_b32_e32 v162, 0xffff0000, v162
	v_lshlrev_b32_e32 v179, 16, v166
	v_and_b32_e32 v166, 0xffff0000, v166
	v_mul_f32_e32 v14, 0xbfb8aa3b, v14
	v_mul_f32_e32 v15, 0xbfb8aa3b, v15
	v_mul_f32_e32 v180, 0xbfb8aa3b, v179
	v_mul_f32_e32 v181, 0xbfb8aa3b, v166
	v_exp_f32_e32 v14, v14
	v_exp_f32_e32 v15, v15
	v_exp_f32_e32 v180, v180
	v_exp_f32_e32 v181, v181
	v_add_f32_e32 v14, 1.0, v14
	v_add_f32_e32 v15, 1.0, v15
	v_add_f32_e32 v180, 1.0, v180
	v_add_f32_e32 v181, 1.0, v181
	v_rcp_f32_e32 v14, v14
	v_rcp_f32_e32 v15, v15
	v_rcp_f32_e32 v180, v180
	v_rcp_f32_e32 v181, v181
	v_mul_f32_e32 v14, v14, v178
	v_mul_f32_e32 v15, v15, v162
	v_mul_f32_e32 v180, v180, v179
	v_mul_f32_e32 v181, v181, v166
	v_mul_f32_e32 v14, v14, v180
	v_mul_f32_e32 v15, v15, v181
	v_lshlrev_b32_e32 v178, 16, v163
	v_and_b32_e32 v163, 0xffff0000, v163
	v_lshlrev_b32_e32 v179, 16, v167
	v_and_b32_e32 v167, 0xffff0000, v167
	v_mul_f32_e32 v16, 0xbfb8aa3b, v16
	v_mul_f32_e32 v17, 0xbfb8aa3b, v17
	v_mul_f32_e32 v180, 0xbfb8aa3b, v179
	v_mul_f32_e32 v181, 0xbfb8aa3b, v167
	v_exp_f32_e32 v16, v16
	v_exp_f32_e32 v17, v17
	v_exp_f32_e32 v180, v180
	v_exp_f32_e32 v181, v181
	v_add_f32_e32 v16, 1.0, v16
	v_add_f32_e32 v17, 1.0, v17
	v_add_f32_e32 v180, 1.0, v180
	v_add_f32_e32 v181, 1.0, v181
	v_rcp_f32_e32 v16, v16
	v_rcp_f32_e32 v17, v17
	v_rcp_f32_e32 v180, v180
	v_rcp_f32_e32 v181, v181
	v_mul_f32_e32 v16, v16, v178
	v_mul_f32_e32 v17, v17, v163
	v_mul_f32_e32 v180, v180, v179
	v_mul_f32_e32 v181, v181, v167
	v_mul_f32_e32 v16, v16, v180
	v_mul_f32_e32 v17, v17, v181
	v_lshlrev_b32_e32 v178, 16, v164
	v_and_b32_e32 v164, 0xffff0000, v164
	v_lshlrev_b32_e32 v179, 16, v168
	v_and_b32_e32 v168, 0xffff0000, v168
	v_mul_f32_e32 v10, 0xbfb8aa3b, v10
	v_mul_f32_e32 v11, 0xbfb8aa3b, v11
	v_mul_f32_e32 v180, 0xbfb8aa3b, v179
	v_mul_f32_e32 v181, 0xbfb8aa3b, v168
	v_exp_f32_e32 v10, v10
	v_exp_f32_e32 v11, v11
	v_exp_f32_e32 v180, v180
	v_exp_f32_e32 v181, v181
	v_add_f32_e32 v10, 1.0, v10
	v_add_f32_e32 v11, 1.0, v11
	v_add_f32_e32 v180, 1.0, v180
	v_add_f32_e32 v181, 1.0, v181
	v_rcp_f32_e32 v10, v10
	v_rcp_f32_e32 v11, v11
	v_rcp_f32_e32 v180, v180
	v_rcp_f32_e32 v181, v181
	v_mul_f32_e32 v10, v10, v178
	v_mul_f32_e32 v11, v11, v164
	v_mul_f32_e32 v180, v180, v179
	v_mul_f32_e32 v181, v181, v168
	v_mul_f32_e32 v10, v10, v180
	v_mul_f32_e32 v11, v11, v181
	v_lshlrev_b32_e32 v178, 16, v165
	v_and_b32_e32 v165, 0xffff0000, v165
	v_lshlrev_b32_e32 v179, 16, v169
	v_and_b32_e32 v169, 0xffff0000, v169
	v_mul_f32_e32 v12, 0xbfb8aa3b, v12
	v_mul_f32_e32 v13, 0xbfb8aa3b, v13
	v_mul_f32_e32 v180, 0xbfb8aa3b, v179
	v_mul_f32_e32 v181, 0xbfb8aa3b, v169
	v_exp_f32_e32 v12, v12
	v_exp_f32_e32 v13, v13
	v_exp_f32_e32 v180, v180
	v_exp_f32_e32 v181, v181
	v_add_f32_e32 v12, 1.0, v12
	v_add_f32_e32 v13, 1.0, v13
	v_add_f32_e32 v180, 1.0, v180
	v_add_f32_e32 v181, 1.0, v181
	v_rcp_f32_e32 v12, v12
	v_rcp_f32_e32 v13, v13
	v_rcp_f32_e32 v180, v180
	v_rcp_f32_e32 v181, v181
	v_mul_f32_e32 v12, v12, v178
	v_mul_f32_e32 v13, v13, v165
	v_mul_f32_e32 v180, v180, v179
	v_mul_f32_e32 v181, v181, v169
	v_mul_f32_e32 v12, v12, v180
	v_mul_f32_e32 v13, v13, v181
	v_cvt_pk_bf16_f32 v14, v14, v15
	v_cvt_pk_bf16_f32 v15, v16, v17
	v_cvt_pk_bf16_f32 v16, v10, v11
	v_cvt_pk_bf16_f32 v17, v12, v13
	global_store_dwordx4 v[146:147], v[14:17], off
	s_waitcnt vmcnt(2)
	v_lshlrev_b32_e32 v178, 16, v170
	v_and_b32_e32 v170, 0xffff0000, v170
	v_lshlrev_b32_e32 v179, 16, v174
	v_and_b32_e32 v174, 0xffff0000, v174
	v_mul_f32_e32 v6, 0xbfb8aa3b, v6
	v_mul_f32_e32 v7, 0xbfb8aa3b, v7
	v_mul_f32_e32 v180, 0xbfb8aa3b, v179
	v_mul_f32_e32 v181, 0xbfb8aa3b, v174
	v_exp_f32_e32 v6, v6
	v_exp_f32_e32 v7, v7
	v_exp_f32_e32 v180, v180
	v_exp_f32_e32 v181, v181
	v_add_f32_e32 v6, 1.0, v6
	v_add_f32_e32 v7, 1.0, v7
	v_add_f32_e32 v180, 1.0, v180
	v_add_f32_e32 v181, 1.0, v181
	v_rcp_f32_e32 v6, v6
	v_rcp_f32_e32 v7, v7
	v_rcp_f32_e32 v180, v180
	v_rcp_f32_e32 v181, v181
	v_mul_f32_e32 v6, v6, v178
	v_mul_f32_e32 v7, v7, v170
	v_mul_f32_e32 v180, v180, v179
	v_mul_f32_e32 v181, v181, v174
	v_mul_f32_e32 v6, v6, v180
	v_mul_f32_e32 v7, v7, v181
	v_lshlrev_b32_e32 v178, 16, v171
	v_and_b32_e32 v171, 0xffff0000, v171
	v_lshlrev_b32_e32 v179, 16, v175
	v_and_b32_e32 v175, 0xffff0000, v175
	v_mul_f32_e32 v8, 0xbfb8aa3b, v8
	v_mul_f32_e32 v9, 0xbfb8aa3b, v9
	v_mul_f32_e32 v180, 0xbfb8aa3b, v179
	v_mul_f32_e32 v181, 0xbfb8aa3b, v175
	v_exp_f32_e32 v8, v8
	v_exp_f32_e32 v9, v9
	v_exp_f32_e32 v180, v180
	v_exp_f32_e32 v181, v181
	v_add_f32_e32 v8, 1.0, v8
	v_add_f32_e32 v9, 1.0, v9
	v_add_f32_e32 v180, 1.0, v180
	v_add_f32_e32 v181, 1.0, v181
	v_rcp_f32_e32 v8, v8
	v_rcp_f32_e32 v9, v9
	v_rcp_f32_e32 v180, v180
	v_rcp_f32_e32 v181, v181
	v_mul_f32_e32 v8, v8, v178
	v_mul_f32_e32 v9, v9, v171
	v_mul_f32_e32 v180, v180, v179
	v_mul_f32_e32 v181, v181, v175
	v_mul_f32_e32 v8, v8, v180
	v_mul_f32_e32 v9, v9, v181
	v_lshlrev_b32_e32 v178, 16, v172
	v_and_b32_e32 v172, 0xffff0000, v172
	v_lshlrev_b32_e32 v179, 16, v176
	v_and_b32_e32 v176, 0xffff0000, v176
	v_mul_f32_e32 v2, 0xbfb8aa3b, v2
	v_mul_f32_e32 v3, 0xbfb8aa3b, v3
	v_mul_f32_e32 v180, 0xbfb8aa3b, v179
	v_mul_f32_e32 v181, 0xbfb8aa3b, v176
	v_exp_f32_e32 v2, v2
	v_exp_f32_e32 v3, v3
	v_exp_f32_e32 v180, v180
	v_exp_f32_e32 v181, v181
	v_add_f32_e32 v2, 1.0, v2
	v_add_f32_e32 v3, 1.0, v3
	v_add_f32_e32 v180, 1.0, v180
	v_add_f32_e32 v181, 1.0, v181
	v_rcp_f32_e32 v2, v2
	v_rcp_f32_e32 v3, v3
	v_rcp_f32_e32 v180, v180
	v_rcp_f32_e32 v181, v181
	v_mul_f32_e32 v2, v2, v178
	v_mul_f32_e32 v3, v3, v172
	v_mul_f32_e32 v180, v180, v179
	v_mul_f32_e32 v181, v181, v176
	v_mul_f32_e32 v2, v2, v180
	v_mul_f32_e32 v3, v3, v181
	v_lshlrev_b32_e32 v178, 16, v173
	v_and_b32_e32 v173, 0xffff0000, v173
	v_lshlrev_b32_e32 v179, 16, v177
	v_and_b32_e32 v177, 0xffff0000, v177
	v_mul_f32_e32 v4, 0xbfb8aa3b, v4
	v_mul_f32_e32 v5, 0xbfb8aa3b, v5
	v_mul_f32_e32 v180, 0xbfb8aa3b, v179
	v_mul_f32_e32 v181, 0xbfb8aa3b, v177
	v_exp_f32_e32 v4, v4
	v_exp_f32_e32 v5, v5
	v_exp_f32_e32 v180, v180
	v_exp_f32_e32 v181, v181
	v_add_f32_e32 v4, 1.0, v4
	v_add_f32_e32 v5, 1.0, v5
	v_add_f32_e32 v180, 1.0, v180
	v_add_f32_e32 v181, 1.0, v181
	v_rcp_f32_e32 v4, v4
	v_rcp_f32_e32 v5, v5
	v_rcp_f32_e32 v180, v180
	v_rcp_f32_e32 v181, v181
	v_mul_f32_e32 v4, v4, v178
	v_mul_f32_e32 v5, v5, v173
	v_mul_f32_e32 v180, v180, v179
	v_mul_f32_e32 v181, v181, v177
	v_mul_f32_e32 v4, v4, v180
	v_mul_f32_e32 v5, v5, v181
	v_cvt_pk_bf16_f32 v6, v6, v7
	v_cvt_pk_bf16_f32 v7, v8, v9
	v_cvt_pk_bf16_f32 v8, v2, v3
	v_cvt_pk_bf16_f32 v9, v4, v5
	global_store_dwordx4 v[146:147], v[6:9], off offset:256
	s_andn2_b64 vcc, exec, s[38:39]
	s_mov_b64 s[4:5], -1
	s_cbranch_vccnz .LBB0_686
	s_andn2_b64 vcc, exec, s[42:43]
	s_cbranch_vccnz .LBB0_685
	s_barrier
	s_branch .LBB0_685
	s_nop 0
	s_nop 0
	s_nop 0
	s_nop 0
	s_nop 0
	s_nop 0
	s_nop 0
	s_nop 0
	s_nop 0
	s_nop 0
	s_nop 0
	s_nop 0
	s_nop 0
	s_nop 0
	s_nop 0
	s_nop 0
	s_nop 0
	s_nop 0
	s_nop 0
	s_nop 0
	s_nop 0
	s_nop 0
	s_nop 0
	s_nop 0
	s_nop 0
	s_nop 0
	s_nop 0
	s_nop 0
	s_nop 0
	s_nop 0
	s_nop 0
	s_nop 0
	s_nop 0
	s_nop 0
	s_nop 0
	s_nop 0
	s_nop 0
	s_nop 0
	s_nop 0
	s_nop 0
	s_nop 0
	s_nop 0
	s_nop 0
	s_nop 0
	s_nop 0
	s_nop 0
	s_nop 0
	s_nop 0
	s_nop 0
	s_nop 0
	s_nop 0
	s_nop 0
	s_nop 0
	s_nop 0
	s_nop 0
	s_nop 0
	s_nop 0
	s_nop 0
	s_nop 0
